# stack5 + GEMM K-loops: back edge rotated (loop-carried scalar updates, exit test and next-iteration head scalars moved in front of the closing barrier; exit path has its own barrier copy)
# baseline (speedup 1.0000x reference)
; #define PG8_STAGE(bufoff, gbase, voff) do { _Pragma("unroll") for (int _i = 0; _i < 2; ++_i) \
;         __builtin_amdgcn_global_load_lds((const unsigned*)((const char*)(gbase) + (voff)[_i]), (PG8_LAS unsigned*)(lds + (bufoff) + ldsw + _i * 8192), 16, 0, 0); } while (0)
; #define PG8_LDA(dst, b, h) do { _Pragma("unroll") for (int m = 0; m < 4; ++m) _Pragma("unroll") for (int k = 0; k < 2; ++k) dst[m][k] = *(const PG8_LAS bf16x8*)(lds + PG8_SA(b, h) + aoff + m * 2048 + k * 1024); } while (0)
; #define PG8_LDB(dst, b, h) do { _Pragma("unroll") for (int n = 0; n < 2; ++n) _Pragma("unroll") for (int k = 0; k < 2; ++k) dst[n][k] = *(const PG8_LAS bf16x8*)(lds + PG8_SB(b, h) + boff + n * 2048 + k * 1024); } while (0)
; #define PG8_MMA(ai, bj, At, Bt) do { __builtin_amdgcn_s_setprio(1); _Pragma("unroll") for (int m = 0; m < 4; ++m) _Pragma("unroll") for (int n = 0; n < 2; ++n) _Pragma("unroll") for (int k = 0; k < 2; ++k) \
;         acc[ai][bj][m][n] = __builtin_amdgcn_mfma_f32_16x16x32_bf16(Bt[n][k], At[m][k], acc[ai][bj][m][n], 0, 0, 0); __builtin_amdgcn_s_setprio(0); } while (0)
; #define PG8_WAIT_V(n) asm volatile("s_waitcnt vmcnt(" #n ")" ::: "memory")
; #define PG8_WAIT_L(n) asm volatile("s_waitcnt lgkmcnt(" #n ")" ::: "memory")
; #define PG8_BAR __builtin_amdgcn_s_barrier()
; #define PG8_SCHED __builtin_amdgcn_sched_barrier(0)
; template <class Epi, class Sched, bool ALIGN_EPI = false, bool SP2 = false>
; __device__ __forceinline__ void gemm_phase(PG8_LAS unsigned char* lds, const Gemm g, const Sched& S, const Epi& E, const int tid_in) {
;     ...
;             PG8_LDB(B0, 0, 0); PG8_LDB(B1, 0, 1); PG8_SCHED; PG8_LDA(At, 0, 0); PG8_STAGE(PG8_SA(1, 1), a1 + hstep, voffA);
;             PG8_WAIT_V(8); PG8_WAIT_L(0); PG8_BAR; PG8_MMA(0, 0, At, B0); PG8_MMA(0, 1, At, B1); PG8_BAR; PG8_SCHED;
.Lrot_92:
	ds_read_b128 v[130:133], v142
	ds_read_b128 v[134:137], v142 offset:1024
	ds_read_b128 v[138:141], v142 offset:2048
	ds_read_b128 v[142:145], v142 offset:3072
	ds_read_b128 v[162:165], v183
	ds_read_b128 v[166:169], v183 offset:1024
	ds_read_b128 v[184:187], v183 offset:2048
	ds_read_b128 v[188:191], v183 offset:3072
	s_add_i32 m0, s26, 0xc000
	ds_read_b128 v[192:195], v174
	ds_read_b128 v[196:199], v174 offset:1024
	ds_read_b128 v[200:203], v174 offset:2048
	ds_read_b128 v[204:207], v174 offset:3072
	ds_read_b128 v[208:211], v174 offset:4096
	ds_read_b128 v[212:215], v174 offset:5120
	ds_read_b128 v[216:219], v174 offset:6144
	ds_read_b128 v[220:223], v174 offset:7168
	global_load_lds_dwordx4 v156, s[6:7]
	s_add_i32 m0, s26, 0xe000
	s_nop 0
	global_load_lds_dwordx4 v158, s[6:7]
	s_cmp_lg_u32 s61, -2
	s_cbranch_scc1 .Lra_n_q1
	s_cmp_lt_u32 s37, 2
	s_cbranch_scc1 .Lra_n_q1
	s_waitcnt vmcnt(32)
	s_branch .Lra_d_q1

; #define PG8_STAGE(bufoff, gbase, voff) do { _Pragma("unroll") for (int _i = 0; _i < 2; ++_i) \
;         __builtin_amdgcn_global_load_lds((const unsigned*)((const char*)(gbase) + (voff)[_i]), (PG8_LAS unsigned*)(lds + (bufoff) + ldsw + _i * 8192), 16, 0, 0); } while (0)
; #define PG8_LDA(dst, b, h) do { _Pragma("unroll") for (int m = 0; m < 4; ++m) _Pragma("unroll") for (int k = 0; k < 2; ++k) dst[m][k] = *(const PG8_LAS bf16x8*)(lds + PG8_SA(b, h) + aoff + m * 2048 + k * 1024); } while (0)
; #define PG8_LDB(dst, b, h) do { _Pragma("unroll") for (int n = 0; n < 2; ++n) _Pragma("unroll") for (int k = 0; k < 2; ++k) dst[n][k] = *(const PG8_LAS bf16x8*)(lds + PG8_SB(b, h) + boff + n * 2048 + k * 1024); } while (0)
; #define PG8_MMA(ai, bj, At, Bt) do { __builtin_amdgcn_s_setprio(1); _Pragma("unroll") for (int m = 0; m < 4; ++m) _Pragma("unroll") for (int n = 0; n < 2; ++n) _Pragma("unroll") for (int k = 0; k < 2; ++k) \
;         acc[ai][bj][m][n] = __builtin_amdgcn_mfma_f32_16x16x32_bf16(Bt[n][k], At[m][k], acc[ai][bj][m][n], 0, 0, 0); __builtin_amdgcn_s_setprio(0); } while (0)
; #define PG8_WAIT_V(n) asm volatile("s_waitcnt vmcnt(" #n ")" ::: "memory")
; #define PG8_WAIT_L(n) asm volatile("s_waitcnt lgkmcnt(" #n ")" ::: "memory")
; #define PG8_BAR __builtin_amdgcn_s_barrier()
; #define PG8_SCHED __builtin_amdgcn_sched_barrier(0)
; template <class Epi, class Sched, bool ALIGN_EPI = false, bool SP2 = false>
; __device__ __forceinline__ void gemm_phase(PG8_LAS unsigned char* lds, const Gemm g, const Sched& S, const Epi& E, const int tid_in) {
;     ...
;             PG8_WAIT_V(8); PG8_WAIT_L(0); PG8_BAR; PG8_MMA(0, 0, At, B0); PG8_MMA(0, 1, At, B1); PG8_BAR; PG8_SCHED;
;             PG8_LDA(At, 0, 1); PG8_STAGE(PG8_SB(0, 0), b2, voffB); PG8_STAGE(PG8_SB(0, 1), b2 + hstep, voffB); PG8_STAGE(PG8_SA(0, 0), a2, voffA);
;             PG8_WAIT_V(8); PG8_WAIT_L(0); PG8_BAR; PG8_MMA(1, 0, At, B0); PG8_MMA(1, 1, At, B1); PG8_BAR; PG8_SCHED;
;             PG8_LDB(B0, 1, 0); PG8_LDB(B1, 1, 1); PG8_SCHED; PG8_LDA(At, 1, 0); PG8_STAGE(PG8_SA(0, 1), a2 + hstep, voffA);
;             PG8_WAIT_V(8); PG8_WAIT_L(0); PG8_BAR; PG8_MMA(0, 0, At, B0); PG8_MMA(0, 1, At, B1); PG8_BAR; PG8_SCHED;
.Lra_d_q2:
	s_waitcnt lgkmcnt(0)
	s_barrier
	s_setprio 1
	s_waitcnt lgkmcnt(0)
	v_mfma_f32_16x16x32_bf16 v[62:65], v[130:133], v[192:195], v[62:65]
	v_mfma_f32_16x16x32_bf16 v[58:61], v[138:141], v[192:195], v[58:61]
	v_mfma_f32_16x16x32_bf16 v[46:49], v[130:133], v[200:203], v[46:49]
	v_mfma_f32_16x16x32_bf16 v[42:45], v[138:141], v[200:203], v[42:45]
	v_mfma_f32_16x16x32_bf16 v[30:33], v[130:133], v[208:211], v[30:33]
	v_mfma_f32_16x16x32_bf16 v[26:29], v[138:141], v[208:211], v[26:29]
	v_mfma_f32_16x16x32_bf16 v[14:17], v[130:133], v[216:219], v[14:17]
	v_mfma_f32_16x16x32_bf16 v[10:13], v[138:141], v[216:219], v[10:13]
	v_mfma_f32_16x16x32_bf16 v[62:65], v[134:137], v[196:199], v[62:65]
	v_mfma_f32_16x16x32_bf16 v[58:61], v[142:145], v[196:199], v[58:61]
	v_mfma_f32_16x16x32_bf16 v[46:49], v[134:137], v[204:207], v[46:49]
	v_mfma_f32_16x16x32_bf16 v[42:45], v[142:145], v[204:207], v[42:45]
	v_mfma_f32_16x16x32_bf16 v[30:33], v[134:137], v[212:215], v[30:33]
	v_mfma_f32_16x16x32_bf16 v[26:29], v[142:145], v[212:215], v[26:29]
	v_mfma_f32_16x16x32_bf16 v[14:17], v[134:137], v[220:223], v[14:17]
	v_mfma_f32_16x16x32_bf16 v[10:13], v[142:145], v[220:223], v[10:13]
	s_setprio 0
	s_setprio 1
	v_mfma_f32_16x16x32_bf16 v[54:57], v[162:165], v[192:195], v[54:57]
	v_mfma_f32_16x16x32_bf16 v[50:53], v[184:187], v[192:195], v[50:53]
	v_mfma_f32_16x16x32_bf16 v[38:41], v[162:165], v[200:203], v[38:41]
	v_mfma_f32_16x16x32_bf16 v[34:37], v[184:187], v[200:203], v[34:37]
	v_mfma_f32_16x16x32_bf16 v[22:25], v[162:165], v[208:211], v[22:25]
	v_mfma_f32_16x16x32_bf16 v[18:21], v[184:187], v[208:211], v[18:21]
	v_mfma_f32_16x16x32_bf16 v[6:9], v[162:165], v[216:219], v[6:9]
	v_mfma_f32_16x16x32_bf16 v[2:5], v[184:187], v[216:219], v[2:5]
	v_mfma_f32_16x16x32_bf16 v[54:57], v[166:169], v[196:199], v[54:57]
	v_mfma_f32_16x16x32_bf16 v[50:53], v[188:191], v[196:199], v[50:53]
	v_mfma_f32_16x16x32_bf16 v[38:41], v[166:169], v[204:207], v[38:41]
	v_mfma_f32_16x16x32_bf16 v[34:37], v[188:191], v[204:207], v[34:37]
	v_mfma_f32_16x16x32_bf16 v[22:25], v[166:169], v[212:215], v[22:25]
	v_mfma_f32_16x16x32_bf16 v[18:21], v[188:191], v[212:215], v[18:21]
	v_mfma_f32_16x16x32_bf16 v[6:9], v[166:169], v[220:223], v[6:9]
	v_mfma_f32_16x16x32_bf16 v[2:5], v[188:191], v[220:223], v[2:5]
	s_setprio 0
	s_barrier
	s_add_i32 s64, 0, 0x18000
	s_add_i32 s71, 0, 0x1c000
	v_add_u32_e32 v142, s64, v171
	v_add_u32_e32 v183, s71, v171
	ds_read_b128 v[130:133], v142
	ds_read_b128 v[134:137], v142 offset:1024
	ds_read_b128 v[138:141], v142 offset:2048
	ds_read_b128 v[142:145], v142 offset:3072
	ds_read_b128 v[162:165], v183
	ds_read_b128 v[166:169], v183 offset:1024
	ds_read_b128 v[184:187], v183 offset:2048
	ds_read_b128 v[188:191], v183 offset:3072
	s_add_u32 s62, s80, 0x40000
	s_addc_u32 s63, s81, 0
	s_mov_b32 m0, s29
	ds_read_b128 v[192:195], v174 offset:32768
	ds_read_b128 v[196:199], v174 offset:33792
	ds_read_b128 v[200:203], v174 offset:34816
	ds_read_b128 v[204:207], v174 offset:35840
	ds_read_b128 v[208:211], v174 offset:36864
	ds_read_b128 v[212:215], v174 offset:37888
	ds_read_b128 v[216:219], v174 offset:38912
	ds_read_b128 v[220:223], v174 offset:39936
	global_load_lds_dwordx4 v146, s[62:63]
	s_mov_b32 m0, s34
	s_nop 0
	global_load_lds_dwordx4 v148, s[62:63]
	s_waitcnt vmcnt(8)
	s_waitcnt lgkmcnt(0)
	s_barrier
	s_setprio 1
	s_waitcnt lgkmcnt(0)
	v_mfma_f32_16x16x32_bf16 v[126:129], v[130:133], v[192:195], v[126:129]
	v_mfma_f32_16x16x32_bf16 v[122:125], v[138:141], v[192:195], v[122:125]
	v_mfma_f32_16x16x32_bf16 v[110:113], v[130:133], v[200:203], v[110:113]
	v_mfma_f32_16x16x32_bf16 v[106:109], v[138:141], v[200:203], v[106:109]
	v_mfma_f32_16x16x32_bf16 v[94:97], v[130:133], v[208:211], v[94:97]
	v_mfma_f32_16x16x32_bf16 v[90:93], v[138:141], v[208:211], v[90:93]
	v_mfma_f32_16x16x32_bf16 v[78:81], v[130:133], v[216:219], v[78:81]
	v_mfma_f32_16x16x32_bf16 v[74:77], v[138:141], v[216:219], v[74:77]
	v_mfma_f32_16x16x32_bf16 v[126:129], v[134:137], v[196:199], v[126:129]
	v_mfma_f32_16x16x32_bf16 v[122:125], v[142:145], v[196:199], v[122:125]
	v_mfma_f32_16x16x32_bf16 v[110:113], v[134:137], v[204:207], v[110:113]
	v_mfma_f32_16x16x32_bf16 v[106:109], v[142:145], v[204:207], v[106:109]
	v_mfma_f32_16x16x32_bf16 v[94:97], v[134:137], v[212:215], v[94:97]
	v_mfma_f32_16x16x32_bf16 v[90:93], v[142:145], v[212:215], v[90:93]
	v_mfma_f32_16x16x32_bf16 v[78:81], v[134:137], v[220:223], v[78:81]
	v_mfma_f32_16x16x32_bf16 v[74:77], v[142:145], v[220:223], v[74:77]
	s_setprio 0
	s_setprio 1
	v_mfma_f32_16x16x32_bf16 v[118:121], v[162:165], v[192:195], v[118:121]
	v_mfma_f32_16x16x32_bf16 v[114:117], v[184:187], v[192:195], v[114:117]
	v_mfma_f32_16x16x32_bf16 v[102:105], v[162:165], v[200:203], v[102:105]
	v_mfma_f32_16x16x32_bf16 v[98:101], v[184:187], v[200:203], v[98:101]
	v_mfma_f32_16x16x32_bf16 v[86:89], v[162:165], v[208:211], v[86:89]
	v_mfma_f32_16x16x32_bf16 v[82:85], v[184:187], v[208:211], v[82:85]
	v_mfma_f32_16x16x32_bf16 v[70:73], v[162:165], v[216:219], v[70:73]
	v_mfma_f32_16x16x32_bf16 v[66:69], v[184:187], v[216:219], v[66:69]
	v_mfma_f32_16x16x32_bf16 v[118:121], v[166:169], v[196:199], v[118:121]
	v_mfma_f32_16x16x32_bf16 v[114:117], v[188:191], v[196:199], v[114:117]
	v_mfma_f32_16x16x32_bf16 v[102:105], v[166:169], v[204:207], v[102:105]
	v_mfma_f32_16x16x32_bf16 v[98:101], v[188:191], v[204:207], v[98:101]
	v_mfma_f32_16x16x32_bf16 v[86:89], v[166:169], v[212:215], v[86:89]
	v_mfma_f32_16x16x32_bf16 v[82:85], v[188:191], v[212:215], v[82:85]
	v_mfma_f32_16x16x32_bf16 v[70:73], v[166:169], v[220:223], v[70:73]
	v_mfma_f32_16x16x32_bf16 v[66:69], v[188:191], v[220:223], v[66:69]
	s_setprio 0
	s_barrier
; #define PG8_STAGE(bufoff, gbase, voff) do { _Pragma("unroll") for (int _i = 0; _i < 2; ++_i) \
;         __builtin_amdgcn_global_load_lds((const unsigned*)((const char*)(gbase) + (voff)[_i]), (PG8_LAS unsigned*)(lds + (bufoff) + ldsw + _i * 8192), 16, 0, 0); } while (0)
; #define PG8_LDA(dst, b, h) do { _Pragma("unroll") for (int m = 0; m < 4; ++m) _Pragma("unroll") for (int k = 0; k < 2; ++k) dst[m][k] = *(const PG8_LAS bf16x8*)(lds + PG8_SA(b, h) + aoff + m * 2048 + k * 1024); } while (0)
; #define PG8_MMA(ai, bj, At, Bt) do { __builtin_amdgcn_s_setprio(1); _Pragma("unroll") for (int m = 0; m < 4; ++m) _Pragma("unroll") for (int n = 0; n < 2; ++n) _Pragma("unroll") for (int k = 0; k < 2; ++k) \
;         acc[ai][bj][m][n] = __builtin_amdgcn_mfma_f32_16x16x32_bf16(Bt[n][k], At[m][k], acc[ai][bj][m][n], 0, 0, 0); __builtin_amdgcn_s_setprio(0); } while (0)
; #define PG8_WAIT_V(n) asm volatile("s_waitcnt vmcnt(" #n ")" ::: "memory")
; #define PG8_WAIT_L(n) asm volatile("s_waitcnt lgkmcnt(" #n ")" ::: "memory")
; #define PG8_BAR __builtin_amdgcn_s_barrier()
; #define PG8_SCHED __builtin_amdgcn_sched_barrier(0)
; template <class Epi, class Sched, bool ALIGN_EPI = false, bool SP2 = false>
; __device__ __forceinline__ void gemm_phase(PG8_LAS unsigned char* lds, const Gemm g, const Sched& S, const Epi& E, const int tid_in) {
;     ...
;         for (int t = 0; t < nt; t += 2) {
;             const bool last = (t == nt - 2);
;             const char* a1 = cA + (size_t)(t + 1) * kstep;
;             const char* a2 = last ? nA : cA + (size_t)(t + 2) * kstep; const char* b2 = last ? nB : cB + (size_t)(t + 2) * kstep;
;             const char* a3 = a2 + kstep; const char* b3 = b2 + kstep;
;             if (last && has_next) S.a_ready(nxt);
;     ...
;             PG8_WAIT_V(8); PG8_WAIT_L(0); PG8_BAR; PG8_MMA(0, 0, At, B0); PG8_MMA(0, 1, At, B1); PG8_BAR; PG8_SCHED;
;             PG8_LDA(At, 1, 1); PG8_STAGE(PG8_SB(1, 0), b3, voffB); PG8_STAGE(PG8_SB(1, 1), b3 + hstep, voffB); PG8_STAGE(PG8_SA(1, 0), a3, voffA);
;             PG8_WAIT_V(8); PG8_WAIT_L(0); PG8_BAR; PG8_MMA(1, 0, At, B0); PG8_MMA(1, 1, At, B1); PG8_BAR; PG8_SCHED;
	s_add_i32 s62, s64, s21
	s_mov_b32 m0, s62
	ds_read_b128 v[192:195], v174 offset:49152
	ds_read_b128 v[196:199], v174 offset:50176
	ds_read_b128 v[200:203], v174 offset:51200
	ds_read_b128 v[204:207], v174 offset:52224
	ds_read_b128 v[208:211], v174 offset:53248
	ds_read_b128 v[212:215], v174 offset:54272
	ds_read_b128 v[216:219], v174 offset:55296
	ds_read_b128 v[220:223], v174 offset:56320
	s_add_u32 s44, s78, 0x80
	s_addc_u32 s45, s79, 0
	global_load_lds_dwordx4 v0, s[44:45]
	s_add_i32 m0, s62, 0x2000
	s_add_u32 s62, s78, 0x40080
	s_addc_u32 s63, s79, 0
	s_add_i32 s64, s71, s21
	global_load_lds_dwordx4 v150, s[44:45]
	s_mov_b32 m0, s64
	s_nop 0
	global_load_lds_dwordx4 v0, s[62:63]
	s_add_i32 m0, s64, 0x2000
	s_nop 0
	global_load_lds_dwordx4 v150, s[62:63]
	s_mov_b32 m0, s35
	s_nop 0
	s_add_u32 s44, s80, 0x80
	s_addc_u32 s45, s81, 0
	global_load_lds_dwordx4 v146, s[44:45]
	s_mov_b32 m0, s36
	s_nop 0
	global_load_lds_dwordx4 v148, s[44:45]
	s_waitcnt vmcnt(8)
	s_waitcnt lgkmcnt(0)
	s_barrier
	s_setprio 1
	s_waitcnt lgkmcnt(0)
	v_mfma_f32_16x16x32_bf16 v[62:65], v[130:133], v[192:195], v[62:65]
	v_mfma_f32_16x16x32_bf16 v[58:61], v[138:141], v[192:195], v[58:61]
	v_mfma_f32_16x16x32_bf16 v[46:49], v[130:133], v[200:203], v[46:49]
	v_mfma_f32_16x16x32_bf16 v[42:45], v[138:141], v[200:203], v[42:45]
	v_mfma_f32_16x16x32_bf16 v[30:33], v[130:133], v[208:211], v[30:33]
	v_mfma_f32_16x16x32_bf16 v[26:29], v[138:141], v[208:211], v[26:29]
	v_mfma_f32_16x16x32_bf16 v[14:17], v[130:133], v[216:219], v[14:17]
	v_mfma_f32_16x16x32_bf16 v[10:13], v[138:141], v[216:219], v[10:13]
	v_mfma_f32_16x16x32_bf16 v[62:65], v[134:137], v[196:199], v[62:65]
	v_mfma_f32_16x16x32_bf16 v[58:61], v[142:145], v[196:199], v[58:61]
	v_mfma_f32_16x16x32_bf16 v[46:49], v[134:137], v[204:207], v[46:49]
	v_mfma_f32_16x16x32_bf16 v[42:45], v[142:145], v[204:207], v[42:45]
	v_mfma_f32_16x16x32_bf16 v[30:33], v[134:137], v[212:215], v[30:33]
	v_mfma_f32_16x16x32_bf16 v[26:29], v[142:145], v[212:215], v[26:29]
	v_mfma_f32_16x16x32_bf16 v[14:17], v[134:137], v[220:223], v[14:17]
	v_mfma_f32_16x16x32_bf16 v[10:13], v[142:145], v[220:223], v[10:13]
	s_setprio 0
	s_setprio 1
	v_mfma_f32_16x16x32_bf16 v[54:57], v[162:165], v[192:195], v[54:57]
	v_mfma_f32_16x16x32_bf16 v[50:53], v[184:187], v[192:195], v[50:53]
	v_mfma_f32_16x16x32_bf16 v[38:41], v[162:165], v[200:203], v[38:41]
	v_mfma_f32_16x16x32_bf16 v[34:37], v[184:187], v[200:203], v[34:37]
	v_mfma_f32_16x16x32_bf16 v[22:25], v[162:165], v[208:211], v[22:25]
	v_mfma_f32_16x16x32_bf16 v[18:21], v[184:187], v[208:211], v[18:21]
	v_mfma_f32_16x16x32_bf16 v[6:9], v[162:165], v[216:219], v[6:9]
	v_mfma_f32_16x16x32_bf16 v[2:5], v[184:187], v[216:219], v[2:5]
	v_mfma_f32_16x16x32_bf16 v[54:57], v[166:169], v[196:199], v[54:57]
	v_mfma_f32_16x16x32_bf16 v[50:53], v[188:191], v[196:199], v[50:53]
	v_mfma_f32_16x16x32_bf16 v[38:41], v[166:169], v[204:207], v[38:41]
	v_mfma_f32_16x16x32_bf16 v[34:37], v[188:191], v[204:207], v[34:37]
	v_mfma_f32_16x16x32_bf16 v[22:25], v[166:169], v[212:215], v[22:25]
	v_mfma_f32_16x16x32_bf16 v[18:21], v[188:191], v[212:215], v[18:21]
	v_mfma_f32_16x16x32_bf16 v[6:9], v[166:169], v[220:223], v[6:9]
	v_mfma_f32_16x16x32_bf16 v[2:5], v[188:191], v[220:223], v[2:5]
	s_setprio 0
	s_add_i32 s61, s61, 2
	s_add_u32 s6, s6, 0x100
	s_addc_u32 s7, s7, 0
	s_add_u32 s59, s59, 0x100
	s_addc_u32 s60, s60, 0
	s_cmp_gt_u32 s61, 13
	s_cbranch_scc1 .Lrotx_92
	s_add_u32 s62, s6, 0xfffc0080
	s_addc_u32 s63, s7, -1
	s_add_i32 s64, 0, 0x10000
	s_cmp_eq_u32 s61, 12
	s_cselect_b32 s81, s11, s63
	s_cselect_b32 s80, s42, s62
	s_cselect_b32 s79, s43, s60
	s_cselect_b32 s78, s58, s59
	s_add_i32 s71, 0, 0x14000
	v_add_u32_e32 v142, s64, v171
	v_add_u32_e32 v183, s71, v171
	s_barrier
	s_branch .Lrot_92
.Lrotx_92:
	s_barrier
	s_mov_b64 s[44:45], 0x80
	s_and_b64 vcc, exec, s[66:67]
	s_cbranch_vccz .LBB0_95
	s_barrier

; #define PG8_STAGE(bufoff, gbase, voff) do { _Pragma("unroll") for (int _i = 0; _i < 2; ++_i) \
;         __builtin_amdgcn_global_load_lds((const unsigned*)((const char*)(gbase) + (voff)[_i]), (PG8_LAS unsigned*)(lds + (bufoff) + ldsw + _i * 8192), 16, 0, 0); } while (0)
; #define PG8_LDA(dst, b, h) do { _Pragma("unroll") for (int m = 0; m < 4; ++m) _Pragma("unroll") for (int k = 0; k < 2; ++k) dst[m][k] = *(const PG8_LAS bf16x8*)(lds + PG8_SA(b, h) + aoff + m * 2048 + k * 1024); } while (0)
; #define PG8_LDB(dst, b, h) do { _Pragma("unroll") for (int n = 0; n < 2; ++n) _Pragma("unroll") for (int k = 0; k < 2; ++k) dst[n][k] = *(const PG8_LAS bf16x8*)(lds + PG8_SB(b, h) + boff + n * 2048 + k * 1024); } while (0)
; #define PG8_MMA(ai, bj, At, Bt) do { __builtin_amdgcn_s_setprio(1); _Pragma("unroll") for (int m = 0; m < 4; ++m) _Pragma("unroll") for (int n = 0; n < 2; ++n) _Pragma("unroll") for (int k = 0; k < 2; ++k) \
;         acc[ai][bj][m][n] = __builtin_amdgcn_mfma_f32_16x16x32_bf16(Bt[n][k], At[m][k], acc[ai][bj][m][n], 0, 0, 0); __builtin_amdgcn_s_setprio(0); } while (0)
; #define PG8_WAIT_V(n) asm volatile("s_waitcnt vmcnt(" #n ")" ::: "memory")
; #define PG8_WAIT_L(n) asm volatile("s_waitcnt lgkmcnt(" #n ")" ::: "memory")
; #define PG8_BAR __builtin_amdgcn_s_barrier()
; #define PG8_SCHED __builtin_amdgcn_sched_barrier(0)
; template <class Epi, class Sched, bool ALIGN_EPI = false, bool SP2 = false>
; __device__ __forceinline__ void gemm_phase(PG8_LAS unsigned char* lds, const Gemm g, const Sched& S, const Epi& E, const int tid_in) {
;     ...
;             PG8_LDB(B0, 0, 0); PG8_LDB(B1, 0, 1); PG8_SCHED; PG8_LDA(At, 0, 0); PG8_STAGE(PG8_SA(1, 1), a1 + hstep, voffA);
;             PG8_WAIT_V(8); PG8_WAIT_L(0); PG8_BAR; PG8_MMA(0, 0, At, B0); PG8_MMA(0, 1, At, B1); PG8_BAR; PG8_SCHED;
.Lrot_485:
	ds_read_b128 v[146:149], v140
	ds_read_b128 v[150:153], v140 offset:1024
	ds_read_b128 v[154:157], v140 offset:2048
	ds_read_b128 v[158:161], v140 offset:3072
	v_add_u32_e32 v140, s61, v143
	ds_read_b128 v[162:165], v140
	ds_read_b128 v[166:169], v140 offset:1024
	ds_read_b128 v[170:173], v140 offset:2048
	ds_read_b128 v[174:177], v140 offset:3072
	s_add_i32 m0, s17, 0xc000
	ds_read_b128 v[178:181], v145
	ds_read_b128 v[182:185], v145 offset:1024
	ds_read_b128 v[186:189], v145 offset:2048
	ds_read_b128 v[190:193], v145 offset:3072
	ds_read_b128 v[194:197], v145 offset:4096
	ds_read_b128 v[198:201], v145 offset:5120
	ds_read_b128 v[202:205], v145 offset:6144
	ds_read_b128 v[206:209], v145 offset:7168
	global_load_lds_dwordx4 v136, s[68:69]
	s_add_i32 m0, s17, 0xe000
	s_nop 0
	global_load_lds_dwordx4 v138, s[68:69]
	s_cmp_lg_u32 s60, -2
	s_cbranch_scc1 .Lra_n_o1
	s_cmp_lt_u32 s37, 2
	s_cbranch_scc1 .Lra_n_o1
	s_waitcnt vmcnt(24)
	s_branch .Lra_d_o1

; #define PG8_STAGE(bufoff, gbase, voff) do { _Pragma("unroll") for (int _i = 0; _i < 2; ++_i) \
;         __builtin_amdgcn_global_load_lds((const unsigned*)((const char*)(gbase) + (voff)[_i]), (PG8_LAS unsigned*)(lds + (bufoff) + ldsw + _i * 8192), 16, 0, 0); } while (0)
; #define PG8_LDA(dst, b, h) do { _Pragma("unroll") for (int m = 0; m < 4; ++m) _Pragma("unroll") for (int k = 0; k < 2; ++k) dst[m][k] = *(const PG8_LAS bf16x8*)(lds + PG8_SA(b, h) + aoff + m * 2048 + k * 1024); } while (0)
; #define PG8_LDB(dst, b, h) do { _Pragma("unroll") for (int n = 0; n < 2; ++n) _Pragma("unroll") for (int k = 0; k < 2; ++k) dst[n][k] = *(const PG8_LAS bf16x8*)(lds + PG8_SB(b, h) + boff + n * 2048 + k * 1024); } while (0)
; #define PG8_MMA(ai, bj, At, Bt) do { __builtin_amdgcn_s_setprio(1); _Pragma("unroll") for (int m = 0; m < 4; ++m) _Pragma("unroll") for (int n = 0; n < 2; ++n) _Pragma("unroll") for (int k = 0; k < 2; ++k) \
;         acc[ai][bj][m][n] = __builtin_amdgcn_mfma_f32_16x16x32_bf16(Bt[n][k], At[m][k], acc[ai][bj][m][n], 0, 0, 0); __builtin_amdgcn_s_setprio(0); } while (0)
; #define PG8_WAIT_V(n) asm volatile("s_waitcnt vmcnt(" #n ")" ::: "memory")
; #define PG8_WAIT_L(n) asm volatile("s_waitcnt lgkmcnt(" #n ")" ::: "memory")
; #define PG8_BAR __builtin_amdgcn_s_barrier()
; #define PG8_SCHED __builtin_amdgcn_sched_barrier(0)
; template <class Epi, class Sched, bool ALIGN_EPI = false, bool SP2 = false>
; __device__ __forceinline__ void gemm_phase(PG8_LAS unsigned char* lds, const Gemm g, const Sched& S, const Epi& E, const int tid_in) {
;     ...
;             PG8_WAIT_V(8); PG8_WAIT_L(0); PG8_BAR; PG8_MMA(0, 0, At, B0); PG8_MMA(0, 1, At, B1); PG8_BAR; PG8_SCHED;
;             PG8_LDA(At, 0, 1); PG8_STAGE(PG8_SB(0, 0), b2, voffB); PG8_STAGE(PG8_SB(0, 1), b2 + hstep, voffB); PG8_STAGE(PG8_SA(0, 0), a2, voffA);
;             PG8_WAIT_V(8); PG8_WAIT_L(0); PG8_BAR; PG8_MMA(1, 0, At, B0); PG8_MMA(1, 1, At, B1); PG8_BAR; PG8_SCHED;
;             PG8_LDB(B0, 1, 0); PG8_LDB(B1, 1, 1); PG8_SCHED; PG8_LDA(At, 1, 0); PG8_STAGE(PG8_SA(0, 1), a2 + hstep, voffA);
;             PG8_WAIT_V(8); PG8_WAIT_L(0); PG8_BAR; PG8_MMA(0, 0, At, B0); PG8_MMA(0, 1, At, B1); PG8_BAR; PG8_SCHED;
.Lra_d_o2:
	s_waitcnt lgkmcnt(0)
	s_barrier
	s_setprio 1
	s_waitcnt lgkmcnt(0)
	v_mfma_f32_16x16x32_bf16 v[62:65], v[146:149], v[178:181], v[62:65]
	v_mfma_f32_16x16x32_bf16 v[58:61], v[154:157], v[178:181], v[58:61]
	v_mfma_f32_16x16x32_bf16 v[54:57], v[146:149], v[186:189], v[54:57]
	v_mfma_f32_16x16x32_bf16 v[46:49], v[154:157], v[186:189], v[46:49]
	v_mfma_f32_16x16x32_bf16 v[38:41], v[146:149], v[194:197], v[38:41]
	v_mfma_f32_16x16x32_bf16 v[30:33], v[154:157], v[194:197], v[30:33]
	v_mfma_f32_16x16x32_bf16 v[22:25], v[146:149], v[202:205], v[22:25]
	v_mfma_f32_16x16x32_bf16 v[14:17], v[154:157], v[202:205], v[14:17]
	v_mfma_f32_16x16x32_bf16 v[62:65], v[150:153], v[182:185], v[62:65]
	v_mfma_f32_16x16x32_bf16 v[58:61], v[158:161], v[182:185], v[58:61]
	v_mfma_f32_16x16x32_bf16 v[54:57], v[150:153], v[190:193], v[54:57]
	v_mfma_f32_16x16x32_bf16 v[46:49], v[158:161], v[190:193], v[46:49]
	v_mfma_f32_16x16x32_bf16 v[38:41], v[150:153], v[198:201], v[38:41]
	v_mfma_f32_16x16x32_bf16 v[30:33], v[158:161], v[198:201], v[30:33]
	v_mfma_f32_16x16x32_bf16 v[22:25], v[150:153], v[206:209], v[22:25]
	v_mfma_f32_16x16x32_bf16 v[14:17], v[158:161], v[206:209], v[14:17]
	s_setprio 0
	s_setprio 1
	v_mfma_f32_16x16x32_bf16 v[50:53], v[162:165], v[178:181], v[50:53]
	v_mfma_f32_16x16x32_bf16 v[42:45], v[170:173], v[178:181], v[42:45]
	v_mfma_f32_16x16x32_bf16 v[34:37], v[162:165], v[186:189], v[34:37]
	v_mfma_f32_16x16x32_bf16 v[26:29], v[170:173], v[186:189], v[26:29]
	v_mfma_f32_16x16x32_bf16 v[18:21], v[162:165], v[194:197], v[18:21]
	v_mfma_f32_16x16x32_bf16 v[10:13], v[170:173], v[194:197], v[10:13]
	v_mfma_f32_16x16x32_bf16 v[6:9], v[162:165], v[202:205], v[6:9]
	v_mfma_f32_16x16x32_bf16 v[2:5], v[170:173], v[202:205], v[2:5]
	v_mfma_f32_16x16x32_bf16 v[50:53], v[166:169], v[182:185], v[50:53]
	v_mfma_f32_16x16x32_bf16 v[42:45], v[174:177], v[182:185], v[42:45]
	v_mfma_f32_16x16x32_bf16 v[34:37], v[166:169], v[190:193], v[34:37]
	v_mfma_f32_16x16x32_bf16 v[26:29], v[174:177], v[190:193], v[26:29]
	v_mfma_f32_16x16x32_bf16 v[18:21], v[166:169], v[198:201], v[18:21]
	v_mfma_f32_16x16x32_bf16 v[10:13], v[174:177], v[198:201], v[10:13]
	v_mfma_f32_16x16x32_bf16 v[6:9], v[166:169], v[206:209], v[6:9]
	v_mfma_f32_16x16x32_bf16 v[2:5], v[174:177], v[206:209], v[2:5]
	s_setprio 0
	s_barrier
	s_add_i32 s61, 0, 0x18000
	s_add_i32 s64, 0, 0x1c000
	v_add_u32_e32 v158, s61, v143
	v_add_u32_e32 v174, s64, v143
	ds_read_b128 v[146:149], v158
	ds_read_b128 v[150:153], v158 offset:1024
	ds_read_b128 v[154:157], v158 offset:2048
	ds_read_b128 v[158:161], v158 offset:3072
	ds_read_b128 v[162:165], v174
	ds_read_b128 v[166:169], v174 offset:1024
	ds_read_b128 v[170:173], v174 offset:2048
	ds_read_b128 v[174:177], v174 offset:3072
	s_add_u32 s62, s72, 0x40000
	s_addc_u32 s63, s73, 0
	s_mov_b32 m0, s29
	ds_read_b128 v[178:181], v145 offset:32768
	ds_read_b128 v[182:185], v145 offset:33792
	ds_read_b128 v[186:189], v145 offset:34816
	ds_read_b128 v[190:193], v145 offset:35840
	ds_read_b128 v[194:197], v145 offset:36864
	ds_read_b128 v[198:201], v145 offset:37888
	ds_read_b128 v[202:205], v145 offset:38912
	ds_read_b128 v[206:209], v145 offset:39936
	global_load_lds_dwordx4 v130, s[62:63]
	s_mov_b32 m0, s34
	s_nop 0
	global_load_lds_dwordx4 v132, s[62:63]
	s_waitcnt vmcnt(8)
	s_waitcnt lgkmcnt(0)
	s_barrier
	s_setprio 1
	s_waitcnt lgkmcnt(0)
	v_mfma_f32_16x16x32_bf16 v[126:129], v[146:149], v[178:181], v[126:129]
	v_mfma_f32_16x16x32_bf16 v[122:125], v[154:157], v[178:181], v[122:125]
	v_mfma_f32_16x16x32_bf16 v[118:121], v[146:149], v[186:189], v[118:121]
	v_mfma_f32_16x16x32_bf16 v[110:113], v[154:157], v[186:189], v[110:113]
	v_mfma_f32_16x16x32_bf16 v[102:105], v[146:149], v[194:197], v[102:105]
	v_mfma_f32_16x16x32_bf16 v[94:97], v[154:157], v[194:197], v[94:97]
	v_mfma_f32_16x16x32_bf16 v[86:89], v[146:149], v[202:205], v[86:89]
	v_mfma_f32_16x16x32_bf16 v[78:81], v[154:157], v[202:205], v[78:81]
	v_mfma_f32_16x16x32_bf16 v[126:129], v[150:153], v[182:185], v[126:129]
	v_mfma_f32_16x16x32_bf16 v[122:125], v[158:161], v[182:185], v[122:125]
	v_mfma_f32_16x16x32_bf16 v[118:121], v[150:153], v[190:193], v[118:121]
	v_mfma_f32_16x16x32_bf16 v[110:113], v[158:161], v[190:193], v[110:113]
	v_mfma_f32_16x16x32_bf16 v[102:105], v[150:153], v[198:201], v[102:105]
	v_mfma_f32_16x16x32_bf16 v[94:97], v[158:161], v[198:201], v[94:97]
	v_mfma_f32_16x16x32_bf16 v[86:89], v[150:153], v[206:209], v[86:89]
	v_mfma_f32_16x16x32_bf16 v[78:81], v[158:161], v[206:209], v[78:81]
	s_setprio 0
	s_setprio 1
	v_mfma_f32_16x16x32_bf16 v[114:117], v[162:165], v[178:181], v[114:117]
	v_mfma_f32_16x16x32_bf16 v[106:109], v[170:173], v[178:181], v[106:109]
	v_mfma_f32_16x16x32_bf16 v[98:101], v[162:165], v[186:189], v[98:101]
	v_mfma_f32_16x16x32_bf16 v[90:93], v[170:173], v[186:189], v[90:93]
	v_mfma_f32_16x16x32_bf16 v[82:85], v[162:165], v[194:197], v[82:85]
	v_mfma_f32_16x16x32_bf16 v[74:77], v[170:173], v[194:197], v[74:77]
	v_mfma_f32_16x16x32_bf16 v[70:73], v[162:165], v[202:205], v[70:73]
	v_mfma_f32_16x16x32_bf16 v[66:69], v[170:173], v[202:205], v[66:69]
	v_mfma_f32_16x16x32_bf16 v[114:117], v[166:169], v[182:185], v[114:117]
	v_mfma_f32_16x16x32_bf16 v[106:109], v[174:177], v[182:185], v[106:109]
	v_mfma_f32_16x16x32_bf16 v[98:101], v[166:169], v[190:193], v[98:101]
	v_mfma_f32_16x16x32_bf16 v[90:93], v[174:177], v[190:193], v[90:93]
	v_mfma_f32_16x16x32_bf16 v[82:85], v[166:169], v[198:201], v[82:85]
	v_mfma_f32_16x16x32_bf16 v[74:77], v[174:177], v[198:201], v[74:77]
	v_mfma_f32_16x16x32_bf16 v[70:73], v[166:169], v[206:209], v[70:73]
	v_mfma_f32_16x16x32_bf16 v[66:69], v[174:177], v[206:209], v[66:69]
	s_setprio 0
	s_barrier
; #define PG8_STAGE(bufoff, gbase, voff) do { _Pragma("unroll") for (int _i = 0; _i < 2; ++_i) \
;         __builtin_amdgcn_global_load_lds((const unsigned*)((const char*)(gbase) + (voff)[_i]), (PG8_LAS unsigned*)(lds + (bufoff) + ldsw + _i * 8192), 16, 0, 0); } while (0)
; #define PG8_LDA(dst, b, h) do { _Pragma("unroll") for (int m = 0; m < 4; ++m) _Pragma("unroll") for (int k = 0; k < 2; ++k) dst[m][k] = *(const PG8_LAS bf16x8*)(lds + PG8_SA(b, h) + aoff + m * 2048 + k * 1024); } while (0)
; #define PG8_MMA(ai, bj, At, Bt) do { __builtin_amdgcn_s_setprio(1); _Pragma("unroll") for (int m = 0; m < 4; ++m) _Pragma("unroll") for (int n = 0; n < 2; ++n) _Pragma("unroll") for (int k = 0; k < 2; ++k) \
;         acc[ai][bj][m][n] = __builtin_amdgcn_mfma_f32_16x16x32_bf16(Bt[n][k], At[m][k], acc[ai][bj][m][n], 0, 0, 0); __builtin_amdgcn_s_setprio(0); } while (0)
; #define PG8_WAIT_V(n) asm volatile("s_waitcnt vmcnt(" #n ")" ::: "memory")
; #define PG8_WAIT_L(n) asm volatile("s_waitcnt lgkmcnt(" #n ")" ::: "memory")
; #define PG8_BAR __builtin_amdgcn_s_barrier()
; #define PG8_SCHED __builtin_amdgcn_sched_barrier(0)
; template <class Epi, class Sched, bool ALIGN_EPI = false, bool SP2 = false>
; __device__ __forceinline__ void gemm_phase(PG8_LAS unsigned char* lds, const Gemm g, const Sched& S, const Epi& E, const int tid_in) {
;     ...
;         for (int t = 0; t < nt; t += 2) {
;             const bool last = (t == nt - 2);
;             const char* a1 = cA + (size_t)(t + 1) * kstep;
;             const char* a2 = last ? nA : cA + (size_t)(t + 2) * kstep; const char* b2 = last ? nB : cB + (size_t)(t + 2) * kstep;
;             const char* a3 = a2 + kstep; const char* b3 = b2 + kstep;
;             if (last && has_next) S.a_ready(nxt);
;     ...
;             PG8_WAIT_V(8); PG8_WAIT_L(0); PG8_BAR; PG8_MMA(0, 0, At, B0); PG8_MMA(0, 1, At, B1); PG8_BAR; PG8_SCHED;
;             PG8_LDA(At, 1, 1); PG8_STAGE(PG8_SB(1, 0), b3, voffB); PG8_STAGE(PG8_SB(1, 1), b3 + hstep, voffB); PG8_STAGE(PG8_SA(1, 0), a3, voffA);
;             PG8_WAIT_V(8); PG8_WAIT_L(0); PG8_BAR; PG8_MMA(1, 0, At, B0); PG8_MMA(1, 1, At, B1); PG8_BAR; PG8_SCHED;
	s_add_i32 s61, s61, s26
	s_mov_b32 m0, s61
	ds_read_b128 v[178:181], v145 offset:49152
	ds_read_b128 v[182:185], v145 offset:50176
	ds_read_b128 v[186:189], v145 offset:51200
	ds_read_b128 v[190:193], v145 offset:52224
	ds_read_b128 v[194:197], v145 offset:53248
	ds_read_b128 v[198:201], v145 offset:54272
	ds_read_b128 v[202:205], v145 offset:55296
	ds_read_b128 v[206:209], v145 offset:56320
	s_add_u32 s44, s70, 0x80
	s_addc_u32 s45, s71, 0
	global_load_lds_dwordx4 v0, s[44:45]
	s_add_i32 m0, s61, 0x2000
	s_add_u32 s62, s70, 0x40080
	s_addc_u32 s63, s71, 0
	s_add_i32 s61, s64, s26
	global_load_lds_dwordx4 v134, s[44:45]
	s_mov_b32 m0, s61
	s_nop 0
	global_load_lds_dwordx4 v0, s[62:63]
	s_add_i32 m0, s61, 0x2000
	s_nop 0
	global_load_lds_dwordx4 v134, s[62:63]
	s_mov_b32 m0, s35
	s_nop 0
	s_add_u32 s44, s72, 0x80
	s_addc_u32 s45, s73, 0
	global_load_lds_dwordx4 v130, s[44:45]
	s_mov_b32 m0, s36
	s_nop 0
	global_load_lds_dwordx4 v132, s[44:45]
	s_waitcnt vmcnt(8)
	s_waitcnt lgkmcnt(0)
	s_barrier
	s_setprio 1
	s_waitcnt lgkmcnt(0)
	v_mfma_f32_16x16x32_bf16 v[62:65], v[146:149], v[178:181], v[62:65]
	v_mfma_f32_16x16x32_bf16 v[58:61], v[154:157], v[178:181], v[58:61]
	v_mfma_f32_16x16x32_bf16 v[54:57], v[146:149], v[186:189], v[54:57]
	v_mfma_f32_16x16x32_bf16 v[46:49], v[154:157], v[186:189], v[46:49]
	v_mfma_f32_16x16x32_bf16 v[38:41], v[146:149], v[194:197], v[38:41]
	v_mfma_f32_16x16x32_bf16 v[30:33], v[154:157], v[194:197], v[30:33]
	v_mfma_f32_16x16x32_bf16 v[22:25], v[146:149], v[202:205], v[22:25]
	v_mfma_f32_16x16x32_bf16 v[14:17], v[154:157], v[202:205], v[14:17]
	v_mfma_f32_16x16x32_bf16 v[62:65], v[150:153], v[182:185], v[62:65]
	v_mfma_f32_16x16x32_bf16 v[58:61], v[158:161], v[182:185], v[58:61]
	v_mfma_f32_16x16x32_bf16 v[54:57], v[150:153], v[190:193], v[54:57]
	v_mfma_f32_16x16x32_bf16 v[46:49], v[158:161], v[190:193], v[46:49]
	v_mfma_f32_16x16x32_bf16 v[38:41], v[150:153], v[198:201], v[38:41]
	v_mfma_f32_16x16x32_bf16 v[30:33], v[158:161], v[198:201], v[30:33]
	v_mfma_f32_16x16x32_bf16 v[22:25], v[150:153], v[206:209], v[22:25]
	v_mfma_f32_16x16x32_bf16 v[14:17], v[158:161], v[206:209], v[14:17]
	s_setprio 0
	s_setprio 1
	v_mfma_f32_16x16x32_bf16 v[50:53], v[162:165], v[178:181], v[50:53]
	v_mfma_f32_16x16x32_bf16 v[42:45], v[170:173], v[178:181], v[42:45]
	v_mfma_f32_16x16x32_bf16 v[34:37], v[162:165], v[186:189], v[34:37]
	v_mfma_f32_16x16x32_bf16 v[26:29], v[170:173], v[186:189], v[26:29]
	v_mfma_f32_16x16x32_bf16 v[18:21], v[162:165], v[194:197], v[18:21]
	v_mfma_f32_16x16x32_bf16 v[10:13], v[170:173], v[194:197], v[10:13]
	v_mfma_f32_16x16x32_bf16 v[6:9], v[162:165], v[202:205], v[6:9]
	v_mfma_f32_16x16x32_bf16 v[2:5], v[170:173], v[202:205], v[2:5]
	v_mfma_f32_16x16x32_bf16 v[50:53], v[166:169], v[182:185], v[50:53]
	v_mfma_f32_16x16x32_bf16 v[42:45], v[174:177], v[182:185], v[42:45]
	v_mfma_f32_16x16x32_bf16 v[34:37], v[166:169], v[190:193], v[34:37]
	v_mfma_f32_16x16x32_bf16 v[26:29], v[174:177], v[190:193], v[26:29]
	v_mfma_f32_16x16x32_bf16 v[18:21], v[166:169], v[198:201], v[18:21]
	v_mfma_f32_16x16x32_bf16 v[10:13], v[174:177], v[198:201], v[10:13]
	v_mfma_f32_16x16x32_bf16 v[6:9], v[166:169], v[206:209], v[6:9]
	v_mfma_f32_16x16x32_bf16 v[2:5], v[174:177], v[206:209], v[2:5]
	s_setprio 0
	s_add_i32 s60, s60, 2
	s_add_u32 s68, s68, 0x100
	s_addc_u32 s69, s69, 0
	s_add_u32 s58, s58, 0x100
	s_addc_u32 s59, s59, 0
	s_cmp_gt_u32 s60, 13
	s_cbranch_scc1 .Lrotx_485
	s_add_u32 s61, s68, 0xfffc0080
	s_addc_u32 s62, s69, -1
	s_add_i32 s63, 0, 0x10000
	s_cmp_eq_u32 s60, 12
	s_cselect_b32 s73, s15, s62
	s_cselect_b32 s72, s42, s61
	v_add_u32_e32 v140, s63, v143
	s_cselect_b32 s71, s13, s59
	s_cselect_b32 s70, s43, s58
	s_add_i32 s61, 0, 0x14000
	s_barrier
	s_branch .Lrot_485
.Lrotx_485:
	s_barrier
	s_mov_b64 s[44:45], 0x80
	s_and_b64 vcc, exec, s[10:11]
	s_cbranch_vccz .LBB0_488
	s_barrier

; #define PG8_STAGE(bufoff, gbase, voff) do { _Pragma("unroll") for (int _i = 0; _i < 2; ++_i) \
;         __builtin_amdgcn_global_load_lds((const unsigned*)((const char*)(gbase) + (voff)[_i]), (PG8_LAS unsigned*)(lds + (bufoff) + ldsw + _i * 8192), 16, 0, 0); } while (0)
; #define PG8_LDA(dst, b, h) do { _Pragma("unroll") for (int m = 0; m < 4; ++m) _Pragma("unroll") for (int k = 0; k < 2; ++k) dst[m][k] = *(const PG8_LAS bf16x8*)(lds + PG8_SA(b, h) + aoff + m * 2048 + k * 1024); } while (0)
; #define PG8_LDB(dst, b, h) do { _Pragma("unroll") for (int n = 0; n < 2; ++n) _Pragma("unroll") for (int k = 0; k < 2; ++k) dst[n][k] = *(const PG8_LAS bf16x8*)(lds + PG8_SB(b, h) + boff + n * 2048 + k * 1024); } while (0)
; #define PG8_MMA(ai, bj, At, Bt) do { __builtin_amdgcn_s_setprio(1); _Pragma("unroll") for (int m = 0; m < 4; ++m) _Pragma("unroll") for (int n = 0; n < 2; ++n) _Pragma("unroll") for (int k = 0; k < 2; ++k) \
;         acc[ai][bj][m][n] = __builtin_amdgcn_mfma_f32_16x16x32_bf16(Bt[n][k], At[m][k], acc[ai][bj][m][n], 0, 0, 0); __builtin_amdgcn_s_setprio(0); } while (0)
; #define PG8_WAIT_V(n) asm volatile("s_waitcnt vmcnt(" #n ")" ::: "memory")
; #define PG8_WAIT_L(n) asm volatile("s_waitcnt lgkmcnt(" #n ")" ::: "memory")
; #define PG8_BAR __builtin_amdgcn_s_barrier()
; #define PG8_SCHED __builtin_amdgcn_sched_barrier(0)
; template <class Epi, class Sched, bool ALIGN_EPI = false, bool SP2 = false>
; __device__ __forceinline__ void gemm_phase(PG8_LAS unsigned char* lds, const Gemm g, const Sched& S, const Epi& E, const int tid_in) {
;     ...
;             PG8_LDB(B0, 0, 0); PG8_LDB(B1, 0, 1); PG8_SCHED; PG8_LDA(At, 0, 0); PG8_STAGE(PG8_SA(1, 1), a1 + hstep, voffA);
;             PG8_WAIT_V(8); PG8_WAIT_L(0); PG8_BAR; PG8_MMA(0, 0, At, B0); PG8_MMA(0, 1, At, B1); PG8_BAR; PG8_SCHED;
.Lrot_622:
	ds_read_b128 v[160:163], v143
	ds_read_b128 v[164:167], v143 offset:1024
	ds_read_b128 v[168:171], v143 offset:2048
	ds_read_b128 v[172:175], v143 offset:3072
	v_add_u32_e32 v143, s76, v145
	ds_read_b128 v[176:179], v143
	ds_read_b128 v[180:183], v143 offset:1024
	ds_read_b128 v[184:187], v143 offset:2048
	ds_read_b128 v[188:191], v143 offset:3072
	s_add_i32 m0, s27, 0xc000
	ds_read_b128 v[192:195], v149
	ds_read_b128 v[196:199], v149 offset:1024
	ds_read_b128 v[200:203], v149 offset:2048
	ds_read_b128 v[204:207], v149 offset:3072
	ds_read_b128 v[208:211], v149 offset:4096
	ds_read_b128 v[212:215], v149 offset:5120
	ds_read_b128 v[216:219], v149 offset:6144
	ds_read_b128 v[220:223], v149 offset:7168
	global_load_lds_dwordx4 v136, s[70:71]
	s_add_i32 m0, s27, 0xe000
	s_nop 0
	global_load_lds_dwordx4 v138, s[70:71]
	s_cmp_lg_u32 s61, -2
	s_cbranch_scc1 .Lra_n_f1
	s_cmp_lt_u32 s38, 2
	s_cbranch_scc1 .Lra_n_f1
	s_waitcnt vmcnt(24)
	s_branch .Lra_d_f1

; #define PG8_STAGE(bufoff, gbase, voff) do { _Pragma("unroll") for (int _i = 0; _i < 2; ++_i) \
;         __builtin_amdgcn_global_load_lds((const unsigned*)((const char*)(gbase) + (voff)[_i]), (PG8_LAS unsigned*)(lds + (bufoff) + ldsw + _i * 8192), 16, 0, 0); } while (0)
; #define PG8_LDA(dst, b, h) do { _Pragma("unroll") for (int m = 0; m < 4; ++m) _Pragma("unroll") for (int k = 0; k < 2; ++k) dst[m][k] = *(const PG8_LAS bf16x8*)(lds + PG8_SA(b, h) + aoff + m * 2048 + k * 1024); } while (0)
; #define PG8_LDB(dst, b, h) do { _Pragma("unroll") for (int n = 0; n < 2; ++n) _Pragma("unroll") for (int k = 0; k < 2; ++k) dst[n][k] = *(const PG8_LAS bf16x8*)(lds + PG8_SB(b, h) + boff + n * 2048 + k * 1024); } while (0)
; #define PG8_MMA(ai, bj, At, Bt) do { __builtin_amdgcn_s_setprio(1); _Pragma("unroll") for (int m = 0; m < 4; ++m) _Pragma("unroll") for (int n = 0; n < 2; ++n) _Pragma("unroll") for (int k = 0; k < 2; ++k) \
;         acc[ai][bj][m][n] = __builtin_amdgcn_mfma_f32_16x16x32_bf16(Bt[n][k], At[m][k], acc[ai][bj][m][n], 0, 0, 0); __builtin_amdgcn_s_setprio(0); } while (0)
; #define PG8_WAIT_V(n) asm volatile("s_waitcnt vmcnt(" #n ")" ::: "memory")
; #define PG8_WAIT_L(n) asm volatile("s_waitcnt lgkmcnt(" #n ")" ::: "memory")
; #define PG8_BAR __builtin_amdgcn_s_barrier()
; #define PG8_SCHED __builtin_amdgcn_sched_barrier(0)
; template <class Epi, class Sched, bool ALIGN_EPI = false, bool SP2 = false>
; __device__ __forceinline__ void gemm_phase(PG8_LAS unsigned char* lds, const Gemm g, const Sched& S, const Epi& E, const int tid_in) {
;     ...
;             PG8_WAIT_V(8); PG8_WAIT_L(0); PG8_BAR; PG8_MMA(0, 0, At, B0); PG8_MMA(0, 1, At, B1); PG8_BAR; PG8_SCHED;
;             PG8_LDA(At, 0, 1); PG8_STAGE(PG8_SB(0, 0), b2, voffB); PG8_STAGE(PG8_SB(0, 1), b2 + hstep, voffB); PG8_STAGE(PG8_SA(0, 0), a2, voffA);
;             PG8_WAIT_V(8); PG8_WAIT_L(0); PG8_BAR; PG8_MMA(1, 0, At, B0); PG8_MMA(1, 1, At, B1); PG8_BAR; PG8_SCHED;
;             PG8_LDB(B0, 1, 0); PG8_LDB(B1, 1, 1); PG8_SCHED; PG8_LDA(At, 1, 0); PG8_STAGE(PG8_SA(0, 1), a2 + hstep, voffA);
;             PG8_WAIT_V(8); PG8_WAIT_L(0); PG8_BAR; PG8_MMA(0, 0, At, B0); PG8_MMA(0, 1, At, B1); PG8_BAR; PG8_SCHED;
.Lra_d_f2:
	s_waitcnt lgkmcnt(0)
	s_barrier
	s_setprio 1
	s_waitcnt lgkmcnt(0)
	v_mfma_f32_16x16x32_bf16 v[62:65], v[160:163], v[192:195], v[62:65]
	v_mfma_f32_16x16x32_bf16 v[54:57], v[168:171], v[192:195], v[54:57]
	v_mfma_f32_16x16x32_bf16 v[46:49], v[160:163], v[200:203], v[46:49]
	v_mfma_f32_16x16x32_bf16 v[38:41], v[168:171], v[200:203], v[38:41]
	v_mfma_f32_16x16x32_bf16 v[30:33], v[160:163], v[208:211], v[30:33]
	v_mfma_f32_16x16x32_bf16 v[22:25], v[168:171], v[208:211], v[22:25]
	v_mfma_f32_16x16x32_bf16 v[14:17], v[160:163], v[216:219], v[14:17]
	v_mfma_f32_16x16x32_bf16 v[6:9], v[168:171], v[216:219], v[6:9]
	v_mfma_f32_16x16x32_bf16 v[62:65], v[164:167], v[196:199], v[62:65]
	v_mfma_f32_16x16x32_bf16 v[54:57], v[172:175], v[196:199], v[54:57]
	v_mfma_f32_16x16x32_bf16 v[46:49], v[164:167], v[204:207], v[46:49]
	v_mfma_f32_16x16x32_bf16 v[38:41], v[172:175], v[204:207], v[38:41]
	v_mfma_f32_16x16x32_bf16 v[30:33], v[164:167], v[212:215], v[30:33]
	v_mfma_f32_16x16x32_bf16 v[22:25], v[172:175], v[212:215], v[22:25]
	v_mfma_f32_16x16x32_bf16 v[14:17], v[164:167], v[220:223], v[14:17]
	v_mfma_f32_16x16x32_bf16 v[6:9], v[172:175], v[220:223], v[6:9]
	s_setprio 0
	s_setprio 1
	v_mfma_f32_16x16x32_bf16 v[58:61], v[176:179], v[192:195], v[58:61]
	v_mfma_f32_16x16x32_bf16 v[50:53], v[184:187], v[192:195], v[50:53]
	v_mfma_f32_16x16x32_bf16 v[42:45], v[176:179], v[200:203], v[42:45]
	v_mfma_f32_16x16x32_bf16 v[34:37], v[184:187], v[200:203], v[34:37]
	v_mfma_f32_16x16x32_bf16 v[26:29], v[176:179], v[208:211], v[26:29]
	v_mfma_f32_16x16x32_bf16 v[18:21], v[184:187], v[208:211], v[18:21]
	v_mfma_f32_16x16x32_bf16 v[10:13], v[176:179], v[216:219], v[10:13]
	v_mfma_f32_16x16x32_bf16 v[2:5], v[184:187], v[216:219], v[2:5]
	v_mfma_f32_16x16x32_bf16 v[58:61], v[180:183], v[196:199], v[58:61]
	v_mfma_f32_16x16x32_bf16 v[50:53], v[188:191], v[196:199], v[50:53]
	v_mfma_f32_16x16x32_bf16 v[42:45], v[180:183], v[204:207], v[42:45]
	v_mfma_f32_16x16x32_bf16 v[34:37], v[188:191], v[204:207], v[34:37]
	v_mfma_f32_16x16x32_bf16 v[26:29], v[180:183], v[212:215], v[26:29]
	v_mfma_f32_16x16x32_bf16 v[18:21], v[188:191], v[212:215], v[18:21]
	v_mfma_f32_16x16x32_bf16 v[10:13], v[180:183], v[220:223], v[10:13]
	v_mfma_f32_16x16x32_bf16 v[2:5], v[188:191], v[220:223], v[2:5]
	s_setprio 0
	s_barrier
	s_add_i32 s64, 0, 0x18000
	v_add_u32_e32 v143, s64, v145
	s_add_i32 s76, 0, 0x1c000
	ds_read_b128 v[160:163], v143
	ds_read_b128 v[164:167], v143 offset:1024
	ds_read_b128 v[168:171], v143 offset:2048
	ds_read_b128 v[172:175], v143 offset:3072
	v_add_u32_e32 v143, s76, v145
	ds_read_b128 v[176:179], v143
	ds_read_b128 v[180:183], v143 offset:1024
	ds_read_b128 v[184:187], v143 offset:2048
	ds_read_b128 v[188:191], v143 offset:3072
	s_add_u32 s62, s74, 0x40000
	s_addc_u32 s63, s75, 0
	s_mov_b32 m0, s34
	ds_read_b128 v[192:195], v149 offset:32768
	ds_read_b128 v[196:199], v149 offset:33792
	ds_read_b128 v[200:203], v149 offset:34816
	ds_read_b128 v[204:207], v149 offset:35840
	ds_read_b128 v[208:211], v149 offset:36864
	ds_read_b128 v[212:215], v149 offset:37888
	ds_read_b128 v[216:219], v149 offset:38912
	ds_read_b128 v[220:223], v149 offset:39936
	global_load_lds_dwordx4 v134, s[62:63]
	s_mov_b32 m0, s35
	s_nop 0
	global_load_lds_dwordx4 v132, s[62:63]
	s_waitcnt vmcnt(8)
	s_waitcnt lgkmcnt(0)
	s_barrier
	s_setprio 1
	s_waitcnt lgkmcnt(0)
	v_mfma_f32_16x16x32_bf16 v[126:129], v[160:163], v[192:195], v[126:129]
	v_mfma_f32_16x16x32_bf16 v[118:121], v[168:171], v[192:195], v[118:121]
	v_mfma_f32_16x16x32_bf16 v[110:113], v[160:163], v[200:203], v[110:113]
	v_mfma_f32_16x16x32_bf16 v[102:105], v[168:171], v[200:203], v[102:105]
	v_mfma_f32_16x16x32_bf16 v[94:97], v[160:163], v[208:211], v[94:97]
	v_mfma_f32_16x16x32_bf16 v[86:89], v[168:171], v[208:211], v[86:89]
	v_mfma_f32_16x16x32_bf16 v[78:81], v[160:163], v[216:219], v[78:81]
	v_mfma_f32_16x16x32_bf16 v[70:73], v[168:171], v[216:219], v[70:73]
	v_mfma_f32_16x16x32_bf16 v[126:129], v[164:167], v[196:199], v[126:129]
	v_mfma_f32_16x16x32_bf16 v[118:121], v[172:175], v[196:199], v[118:121]
	v_mfma_f32_16x16x32_bf16 v[110:113], v[164:167], v[204:207], v[110:113]
	v_mfma_f32_16x16x32_bf16 v[102:105], v[172:175], v[204:207], v[102:105]
	v_mfma_f32_16x16x32_bf16 v[94:97], v[164:167], v[212:215], v[94:97]
	v_mfma_f32_16x16x32_bf16 v[86:89], v[172:175], v[212:215], v[86:89]
	v_mfma_f32_16x16x32_bf16 v[78:81], v[164:167], v[220:223], v[78:81]
	v_mfma_f32_16x16x32_bf16 v[70:73], v[172:175], v[220:223], v[70:73]
	s_setprio 0
	s_setprio 1
	v_mfma_f32_16x16x32_bf16 v[122:125], v[176:179], v[192:195], v[122:125]
	v_mfma_f32_16x16x32_bf16 v[114:117], v[184:187], v[192:195], v[114:117]
	v_mfma_f32_16x16x32_bf16 v[106:109], v[176:179], v[200:203], v[106:109]
	v_mfma_f32_16x16x32_bf16 v[98:101], v[184:187], v[200:203], v[98:101]
	v_mfma_f32_16x16x32_bf16 v[90:93], v[176:179], v[208:211], v[90:93]
	v_mfma_f32_16x16x32_bf16 v[82:85], v[184:187], v[208:211], v[82:85]
	v_mfma_f32_16x16x32_bf16 v[74:77], v[176:179], v[216:219], v[74:77]
	v_mfma_f32_16x16x32_bf16 v[66:69], v[184:187], v[216:219], v[66:69]
	v_mfma_f32_16x16x32_bf16 v[122:125], v[180:183], v[196:199], v[122:125]
	v_mfma_f32_16x16x32_bf16 v[114:117], v[188:191], v[196:199], v[114:117]
	v_mfma_f32_16x16x32_bf16 v[106:109], v[180:183], v[204:207], v[106:109]
	v_mfma_f32_16x16x32_bf16 v[98:101], v[188:191], v[204:207], v[98:101]
	v_mfma_f32_16x16x32_bf16 v[90:93], v[180:183], v[212:215], v[90:93]
	v_mfma_f32_16x16x32_bf16 v[82:85], v[188:191], v[212:215], v[82:85]
	v_mfma_f32_16x16x32_bf16 v[74:77], v[180:183], v[220:223], v[74:77]
	v_mfma_f32_16x16x32_bf16 v[66:69], v[188:191], v[220:223], v[66:69]
	s_setprio 0
	s_barrier
; #define PG8_STAGE(bufoff, gbase, voff) do { _Pragma("unroll") for (int _i = 0; _i < 2; ++_i) \
;         __builtin_amdgcn_global_load_lds((const unsigned*)((const char*)(gbase) + (voff)[_i]), (PG8_LAS unsigned*)(lds + (bufoff) + ldsw + _i * 8192), 16, 0, 0); } while (0)
; #define PG8_LDA(dst, b, h) do { _Pragma("unroll") for (int m = 0; m < 4; ++m) _Pragma("unroll") for (int k = 0; k < 2; ++k) dst[m][k] = *(const PG8_LAS bf16x8*)(lds + PG8_SA(b, h) + aoff + m * 2048 + k * 1024); } while (0)
; #define PG8_MMA(ai, bj, At, Bt) do { __builtin_amdgcn_s_setprio(1); _Pragma("unroll") for (int m = 0; m < 4; ++m) _Pragma("unroll") for (int n = 0; n < 2; ++n) _Pragma("unroll") for (int k = 0; k < 2; ++k) \
;         acc[ai][bj][m][n] = __builtin_amdgcn_mfma_f32_16x16x32_bf16(Bt[n][k], At[m][k], acc[ai][bj][m][n], 0, 0, 0); __builtin_amdgcn_s_setprio(0); } while (0)
; #define PG8_WAIT_V(n) asm volatile("s_waitcnt vmcnt(" #n ")" ::: "memory")
; #define PG8_WAIT_L(n) asm volatile("s_waitcnt lgkmcnt(" #n ")" ::: "memory")
; #define PG8_BAR __builtin_amdgcn_s_barrier()
; #define PG8_SCHED __builtin_amdgcn_sched_barrier(0)
; template <class Epi, class Sched, bool ALIGN_EPI = false, bool SP2 = false>
; __device__ __forceinline__ void gemm_phase(PG8_LAS unsigned char* lds, const Gemm g, const Sched& S, const Epi& E, const int tid_in) {
;     ...
;         for (int t = 0; t < nt; t += 2) {
;             const bool last = (t == nt - 2);
;             const char* a1 = cA + (size_t)(t + 1) * kstep;
;             const char* a2 = last ? nA : cA + (size_t)(t + 2) * kstep; const char* b2 = last ? nB : cB + (size_t)(t + 2) * kstep;
;             const char* a3 = a2 + kstep; const char* b3 = b2 + kstep;
;             if (last && has_next) S.a_ready(nxt);
;     ...
;             PG8_WAIT_V(8); PG8_WAIT_L(0); PG8_BAR; PG8_MMA(0, 0, At, B0); PG8_MMA(0, 1, At, B1); PG8_BAR; PG8_SCHED;
;             PG8_LDA(At, 1, 1); PG8_STAGE(PG8_SB(1, 0), b3, voffB); PG8_STAGE(PG8_SB(1, 1), b3 + hstep, voffB); PG8_STAGE(PG8_SA(1, 0), a3, voffA);
;             PG8_WAIT_V(8); PG8_WAIT_L(0); PG8_BAR; PG8_MMA(1, 0, At, B0); PG8_MMA(1, 1, At, B1); PG8_BAR; PG8_SCHED;
	s_add_i32 s62, s64, s21
	s_mov_b32 m0, s62
	ds_read_b128 v[192:195], v149 offset:49152
	ds_read_b128 v[196:199], v149 offset:50176
	ds_read_b128 v[200:203], v149 offset:51200
	ds_read_b128 v[204:207], v149 offset:52224
	ds_read_b128 v[208:211], v149 offset:53248
	ds_read_b128 v[212:215], v149 offset:54272
	ds_read_b128 v[216:219], v149 offset:55296
	ds_read_b128 v[220:223], v149 offset:56320
	s_add_u32 s44, s72, 0x80
	s_addc_u32 s45, s73, 0
	global_load_lds_dwordx4 v0, s[44:45]
	s_add_i32 m0, s62, 0x2000
	s_add_u32 s62, s72, 0x40080
	s_addc_u32 s63, s73, 0
	s_add_i32 s64, s76, s21
	global_load_lds_dwordx4 v130, s[44:45]
	s_mov_b32 m0, s64
	s_nop 0
	global_load_lds_dwordx4 v0, s[62:63]
	s_add_i32 m0, s64, 0x2000
	s_nop 0
	global_load_lds_dwordx4 v130, s[62:63]
	s_mov_b32 m0, s36
	s_nop 0
	s_add_u32 s44, s74, 0x80
	s_addc_u32 s45, s75, 0
	global_load_lds_dwordx4 v134, s[44:45]
	s_mov_b32 m0, s37
	s_nop 0
	global_load_lds_dwordx4 v132, s[44:45]
	s_waitcnt vmcnt(8)
	s_waitcnt lgkmcnt(0)
	s_barrier
	s_setprio 1
	s_waitcnt lgkmcnt(0)
	v_mfma_f32_16x16x32_bf16 v[62:65], v[160:163], v[192:195], v[62:65]
	v_mfma_f32_16x16x32_bf16 v[54:57], v[168:171], v[192:195], v[54:57]
	v_mfma_f32_16x16x32_bf16 v[46:49], v[160:163], v[200:203], v[46:49]
	v_mfma_f32_16x16x32_bf16 v[38:41], v[168:171], v[200:203], v[38:41]
	v_mfma_f32_16x16x32_bf16 v[30:33], v[160:163], v[208:211], v[30:33]
	v_mfma_f32_16x16x32_bf16 v[22:25], v[168:171], v[208:211], v[22:25]
	v_mfma_f32_16x16x32_bf16 v[14:17], v[160:163], v[216:219], v[14:17]
	v_mfma_f32_16x16x32_bf16 v[6:9], v[168:171], v[216:219], v[6:9]
	v_mfma_f32_16x16x32_bf16 v[62:65], v[164:167], v[196:199], v[62:65]
	v_mfma_f32_16x16x32_bf16 v[54:57], v[172:175], v[196:199], v[54:57]
	v_mfma_f32_16x16x32_bf16 v[46:49], v[164:167], v[204:207], v[46:49]
	v_mfma_f32_16x16x32_bf16 v[38:41], v[172:175], v[204:207], v[38:41]
	v_mfma_f32_16x16x32_bf16 v[30:33], v[164:167], v[212:215], v[30:33]
	v_mfma_f32_16x16x32_bf16 v[22:25], v[172:175], v[212:215], v[22:25]
	v_mfma_f32_16x16x32_bf16 v[14:17], v[164:167], v[220:223], v[14:17]
	v_mfma_f32_16x16x32_bf16 v[6:9], v[172:175], v[220:223], v[6:9]
	s_setprio 0
	s_setprio 1
	v_mfma_f32_16x16x32_bf16 v[58:61], v[176:179], v[192:195], v[58:61]
	v_mfma_f32_16x16x32_bf16 v[50:53], v[184:187], v[192:195], v[50:53]
	v_mfma_f32_16x16x32_bf16 v[42:45], v[176:179], v[200:203], v[42:45]
	v_mfma_f32_16x16x32_bf16 v[34:37], v[184:187], v[200:203], v[34:37]
	v_mfma_f32_16x16x32_bf16 v[26:29], v[176:179], v[208:211], v[26:29]
	v_mfma_f32_16x16x32_bf16 v[18:21], v[184:187], v[208:211], v[18:21]
	v_mfma_f32_16x16x32_bf16 v[10:13], v[176:179], v[216:219], v[10:13]
	v_mfma_f32_16x16x32_bf16 v[2:5], v[184:187], v[216:219], v[2:5]
	v_mfma_f32_16x16x32_bf16 v[58:61], v[180:183], v[196:199], v[58:61]
	v_mfma_f32_16x16x32_bf16 v[50:53], v[188:191], v[196:199], v[50:53]
	v_mfma_f32_16x16x32_bf16 v[42:45], v[180:183], v[204:207], v[42:45]
	v_mfma_f32_16x16x32_bf16 v[34:37], v[188:191], v[204:207], v[34:37]
	v_mfma_f32_16x16x32_bf16 v[26:29], v[180:183], v[212:215], v[26:29]
	v_mfma_f32_16x16x32_bf16 v[18:21], v[188:191], v[212:215], v[18:21]
	v_mfma_f32_16x16x32_bf16 v[10:13], v[180:183], v[220:223], v[10:13]
	v_mfma_f32_16x16x32_bf16 v[2:5], v[188:191], v[220:223], v[2:5]
	s_setprio 0
	s_add_i32 s61, s61, 2
	s_add_u32 s70, s70, 0x100
	s_addc_u32 s71, s71, 0
	s_add_u32 s59, s59, 0x100
	s_addc_u32 s60, s60, 0
	s_cmp_gt_u32 s61, 13
	s_cbranch_scc1 .Lrotx_622
	s_add_u32 s62, s70, 0xfffc0080
	s_addc_u32 s63, s71, -1
	s_add_i32 s64, 0, 0x10000
	s_cmp_eq_u32 s61, 12
	s_cselect_b32 s75, s7, s63
	s_cselect_b32 s74, s43, s62
	v_add_u32_e32 v143, s64, v145
	s_cselect_b32 s73, s19, s60
	s_cselect_b32 s72, s58, s59
	s_add_i32 s76, 0, 0x14000
	s_barrier
	s_branch .Lrot_622
.Lrotx_622:
	s_barrier
	s_mov_b64 s[44:45], 0x80
	s_and_b64 vcc, exec, s[16:17]
	s_cbranch_vccz .LBB0_625
	s_barrier

; #define PG8_STAGE(bufoff, gbase, voff) do { _Pragma("unroll") for (int _i = 0; _i < 2; ++_i) \
;         __builtin_amdgcn_global_load_lds((const unsigned*)((const char*)(gbase) + (voff)[_i]), (PG8_LAS unsigned*)(lds + (bufoff) + ldsw + _i * 8192), 16, 0, 0); } while (0)
; #define PG8_LDA(dst, b, h) do { _Pragma("unroll") for (int m = 0; m < 4; ++m) _Pragma("unroll") for (int k = 0; k < 2; ++k) dst[m][k] = *(const PG8_LAS bf16x8*)(lds + PG8_SA(b, h) + aoff + m * 2048 + k * 1024); } while (0)
; #define PG8_LDB(dst, b, h) do { _Pragma("unroll") for (int n = 0; n < 2; ++n) _Pragma("unroll") for (int k = 0; k < 2; ++k) dst[n][k] = *(const PG8_LAS bf16x8*)(lds + PG8_SB(b, h) + boff + n * 2048 + k * 1024); } while (0)
; #define PG8_MMA(ai, bj, At, Bt) do { __builtin_amdgcn_s_setprio(1); _Pragma("unroll") for (int m = 0; m < 4; ++m) _Pragma("unroll") for (int n = 0; n < 2; ++n) _Pragma("unroll") for (int k = 0; k < 2; ++k) \
;         acc[ai][bj][m][n] = __builtin_amdgcn_mfma_f32_16x16x32_bf16(Bt[n][k], At[m][k], acc[ai][bj][m][n], 0, 0, 0); __builtin_amdgcn_s_setprio(0); } while (0)
; #define PG8_WAIT_V(n) asm volatile("s_waitcnt vmcnt(" #n ")" ::: "memory")
; #define PG8_WAIT_L(n) asm volatile("s_waitcnt lgkmcnt(" #n ")" ::: "memory")
; #define PG8_BAR __builtin_amdgcn_s_barrier()
; #define PG8_SCHED __builtin_amdgcn_sched_barrier(0)
; template <class Epi, class Sched, bool ALIGN_EPI = false, bool SP2 = false>
; __device__ __forceinline__ void gemm_phase(PG8_LAS unsigned char* lds, const Gemm g, const Sched& S, const Epi& E, const int tid_in) {
;     ...
;             PG8_LDB(B0, 0, 0); PG8_LDB(B1, 0, 1); PG8_SCHED; PG8_LDA(At, 0, 0); PG8_STAGE(PG8_SA(1, 1), a1 + hstep, voffA);
;             PG8_WAIT_V(8); PG8_WAIT_L(0); PG8_BAR; PG8_MMA(0, 0, At, B0); PG8_MMA(0, 1, At, B1); PG8_BAR; PG8_SCHED;
.Lrot_703:
	ds_read_b128 v[146:149], v140
	ds_read_b128 v[150:153], v140 offset:1024
	ds_read_b128 v[154:157], v140 offset:2048
	ds_read_b128 v[158:161], v140 offset:3072
	v_add_u32_e32 v140, s71, v143
	ds_read_b128 v[162:165], v140
	ds_read_b128 v[166:169], v140 offset:1024
	ds_read_b128 v[170:173], v140 offset:2048
	ds_read_b128 v[174:177], v140 offset:3072
	s_add_i32 m0, s34, 0xc000
	ds_read_b128 v[178:181], v145
	ds_read_b128 v[182:185], v145 offset:1024
	ds_read_b128 v[186:189], v145 offset:2048
	ds_read_b128 v[190:193], v145 offset:3072
	ds_read_b128 v[194:197], v145 offset:4096
	ds_read_b128 v[198:201], v145 offset:5120
	ds_read_b128 v[202:205], v145 offset:6144
	ds_read_b128 v[206:209], v145 offset:7168
	global_load_lds_dwordx4 v136, s[18:19]
	s_add_i32 m0, s34, 0xe000
	s_nop 0
	global_load_lds_dwordx4 v138, s[18:19]
	s_cmp_lg_u32 s64, -2
	s_cbranch_scc1 .Lra_n_d1
	s_cmp_lt_u32 s43, 2
	s_cbranch_scc1 .Lra_n_d1
	s_waitcnt vmcnt(24)
	s_branch .Lra_d_d1

; #define PG8_STAGE(bufoff, gbase, voff) do { _Pragma("unroll") for (int _i = 0; _i < 2; ++_i) \
;         __builtin_amdgcn_global_load_lds((const unsigned*)((const char*)(gbase) + (voff)[_i]), (PG8_LAS unsigned*)(lds + (bufoff) + ldsw + _i * 8192), 16, 0, 0); } while (0)
; #define PG8_LDA(dst, b, h) do { _Pragma("unroll") for (int m = 0; m < 4; ++m) _Pragma("unroll") for (int k = 0; k < 2; ++k) dst[m][k] = *(const PG8_LAS bf16x8*)(lds + PG8_SA(b, h) + aoff + m * 2048 + k * 1024); } while (0)
; #define PG8_LDB(dst, b, h) do { _Pragma("unroll") for (int n = 0; n < 2; ++n) _Pragma("unroll") for (int k = 0; k < 2; ++k) dst[n][k] = *(const PG8_LAS bf16x8*)(lds + PG8_SB(b, h) + boff + n * 2048 + k * 1024); } while (0)
; #define PG8_MMA(ai, bj, At, Bt) do { __builtin_amdgcn_s_setprio(1); _Pragma("unroll") for (int m = 0; m < 4; ++m) _Pragma("unroll") for (int n = 0; n < 2; ++n) _Pragma("unroll") for (int k = 0; k < 2; ++k) \
;         acc[ai][bj][m][n] = __builtin_amdgcn_mfma_f32_16x16x32_bf16(Bt[n][k], At[m][k], acc[ai][bj][m][n], 0, 0, 0); __builtin_amdgcn_s_setprio(0); } while (0)
; #define PG8_WAIT_V(n) asm volatile("s_waitcnt vmcnt(" #n ")" ::: "memory")
; #define PG8_WAIT_L(n) asm volatile("s_waitcnt lgkmcnt(" #n ")" ::: "memory")
; #define PG8_BAR __builtin_amdgcn_s_barrier()
; #define PG8_SCHED __builtin_amdgcn_sched_barrier(0)
; template <class Epi, class Sched, bool ALIGN_EPI = false, bool SP2 = false>
; __device__ __forceinline__ void gemm_phase(PG8_LAS unsigned char* lds, const Gemm g, const Sched& S, const Epi& E, const int tid_in) {
;     ...
;             PG8_WAIT_V(8); PG8_WAIT_L(0); PG8_BAR; PG8_MMA(0, 0, At, B0); PG8_MMA(0, 1, At, B1); PG8_BAR; PG8_SCHED;
;             PG8_LDA(At, 0, 1); PG8_STAGE(PG8_SB(0, 0), b2, voffB); PG8_STAGE(PG8_SB(0, 1), b2 + hstep, voffB); PG8_STAGE(PG8_SA(0, 0), a2, voffA);
;             PG8_WAIT_V(8); PG8_WAIT_L(0); PG8_BAR; PG8_MMA(1, 0, At, B0); PG8_MMA(1, 1, At, B1); PG8_BAR; PG8_SCHED;
;             PG8_LDB(B0, 1, 0); PG8_LDB(B1, 1, 1); PG8_SCHED; PG8_LDA(At, 1, 0); PG8_STAGE(PG8_SA(0, 1), a2 + hstep, voffA);
;             PG8_WAIT_V(8); PG8_WAIT_L(0); PG8_BAR; PG8_MMA(0, 0, At, B0); PG8_MMA(0, 1, At, B1); PG8_BAR; PG8_SCHED;
.Lra_d_d2:
	s_waitcnt lgkmcnt(0)
	s_barrier
	s_setprio 1
	s_waitcnt lgkmcnt(0)
	v_mfma_f32_16x16x32_bf16 v[62:65], v[146:149], v[178:181], v[62:65]
	v_mfma_f32_16x16x32_bf16 v[58:61], v[154:157], v[178:181], v[58:61]
	v_mfma_f32_16x16x32_bf16 v[54:57], v[146:149], v[186:189], v[54:57]
	v_mfma_f32_16x16x32_bf16 v[46:49], v[154:157], v[186:189], v[46:49]
	v_mfma_f32_16x16x32_bf16 v[38:41], v[146:149], v[194:197], v[38:41]
	v_mfma_f32_16x16x32_bf16 v[30:33], v[154:157], v[194:197], v[30:33]
	v_mfma_f32_16x16x32_bf16 v[22:25], v[146:149], v[202:205], v[22:25]
	v_mfma_f32_16x16x32_bf16 v[14:17], v[154:157], v[202:205], v[14:17]
	v_mfma_f32_16x16x32_bf16 v[62:65], v[150:153], v[182:185], v[62:65]
	v_mfma_f32_16x16x32_bf16 v[58:61], v[158:161], v[182:185], v[58:61]
	v_mfma_f32_16x16x32_bf16 v[54:57], v[150:153], v[190:193], v[54:57]
	v_mfma_f32_16x16x32_bf16 v[46:49], v[158:161], v[190:193], v[46:49]
	v_mfma_f32_16x16x32_bf16 v[38:41], v[150:153], v[198:201], v[38:41]
	v_mfma_f32_16x16x32_bf16 v[30:33], v[158:161], v[198:201], v[30:33]
	v_mfma_f32_16x16x32_bf16 v[22:25], v[150:153], v[206:209], v[22:25]
	v_mfma_f32_16x16x32_bf16 v[14:17], v[158:161], v[206:209], v[14:17]
	s_setprio 0
	s_setprio 1
	v_mfma_f32_16x16x32_bf16 v[50:53], v[162:165], v[178:181], v[50:53]
	v_mfma_f32_16x16x32_bf16 v[42:45], v[170:173], v[178:181], v[42:45]
	v_mfma_f32_16x16x32_bf16 v[34:37], v[162:165], v[186:189], v[34:37]
	v_mfma_f32_16x16x32_bf16 v[26:29], v[170:173], v[186:189], v[26:29]
	v_mfma_f32_16x16x32_bf16 v[18:21], v[162:165], v[194:197], v[18:21]
	v_mfma_f32_16x16x32_bf16 v[10:13], v[170:173], v[194:197], v[10:13]
	v_mfma_f32_16x16x32_bf16 v[6:9], v[162:165], v[202:205], v[6:9]
	v_mfma_f32_16x16x32_bf16 v[2:5], v[170:173], v[202:205], v[2:5]
	v_mfma_f32_16x16x32_bf16 v[50:53], v[166:169], v[182:185], v[50:53]
	v_mfma_f32_16x16x32_bf16 v[42:45], v[174:177], v[182:185], v[42:45]
	v_mfma_f32_16x16x32_bf16 v[34:37], v[166:169], v[190:193], v[34:37]
	v_mfma_f32_16x16x32_bf16 v[26:29], v[174:177], v[190:193], v[26:29]
	v_mfma_f32_16x16x32_bf16 v[18:21], v[166:169], v[198:201], v[18:21]
	v_mfma_f32_16x16x32_bf16 v[10:13], v[174:177], v[198:201], v[10:13]
	v_mfma_f32_16x16x32_bf16 v[6:9], v[166:169], v[206:209], v[6:9]
	v_mfma_f32_16x16x32_bf16 v[2:5], v[174:177], v[206:209], v[2:5]
	s_setprio 0
	s_barrier
	s_add_i32 s70, 0, 0x18000
	s_add_i32 s71, 0, 0x1c000
	v_add_u32_e32 v158, s70, v143
	v_add_u32_e32 v174, s71, v143
	ds_read_b128 v[146:149], v158
	ds_read_b128 v[150:153], v158 offset:1024
	ds_read_b128 v[154:157], v158 offset:2048
	ds_read_b128 v[158:161], v158 offset:3072
	ds_read_b128 v[162:165], v174
	ds_read_b128 v[166:169], v174 offset:1024
	ds_read_b128 v[170:173], v174 offset:2048
	ds_read_b128 v[174:177], v174 offset:3072
	s_add_u32 s18, s68, 0xb0000
	s_addc_u32 s19, s69, 0
	s_mov_b32 m0, s36
	ds_read_b128 v[178:181], v145 offset:32768
	ds_read_b128 v[182:185], v145 offset:33792
	ds_read_b128 v[186:189], v145 offset:34816
	ds_read_b128 v[190:193], v145 offset:35840
	ds_read_b128 v[194:197], v145 offset:36864
	ds_read_b128 v[198:201], v145 offset:37888
	ds_read_b128 v[202:205], v145 offset:38912
	ds_read_b128 v[206:209], v145 offset:39936
	global_load_lds_dwordx4 v130, s[18:19]
	s_mov_b32 m0, s37
	s_nop 0
	global_load_lds_dwordx4 v132, s[18:19]
	s_waitcnt vmcnt(8)
	s_waitcnt lgkmcnt(0)
	s_barrier
	s_setprio 1
	s_waitcnt lgkmcnt(0)
	v_mfma_f32_16x16x32_bf16 v[126:129], v[146:149], v[178:181], v[126:129]
	v_mfma_f32_16x16x32_bf16 v[122:125], v[154:157], v[178:181], v[122:125]
	v_mfma_f32_16x16x32_bf16 v[118:121], v[146:149], v[186:189], v[118:121]
	v_mfma_f32_16x16x32_bf16 v[110:113], v[154:157], v[186:189], v[110:113]
	v_mfma_f32_16x16x32_bf16 v[102:105], v[146:149], v[194:197], v[102:105]
	v_mfma_f32_16x16x32_bf16 v[94:97], v[154:157], v[194:197], v[94:97]
	v_mfma_f32_16x16x32_bf16 v[86:89], v[146:149], v[202:205], v[86:89]
	v_mfma_f32_16x16x32_bf16 v[78:81], v[154:157], v[202:205], v[78:81]
	v_mfma_f32_16x16x32_bf16 v[126:129], v[150:153], v[182:185], v[126:129]
	v_mfma_f32_16x16x32_bf16 v[122:125], v[158:161], v[182:185], v[122:125]
	v_mfma_f32_16x16x32_bf16 v[118:121], v[150:153], v[190:193], v[118:121]
	v_mfma_f32_16x16x32_bf16 v[110:113], v[158:161], v[190:193], v[110:113]
	v_mfma_f32_16x16x32_bf16 v[102:105], v[150:153], v[198:201], v[102:105]
	v_mfma_f32_16x16x32_bf16 v[94:97], v[158:161], v[198:201], v[94:97]
	v_mfma_f32_16x16x32_bf16 v[86:89], v[150:153], v[206:209], v[86:89]
	v_mfma_f32_16x16x32_bf16 v[78:81], v[158:161], v[206:209], v[78:81]
	s_setprio 0
	s_setprio 1
	v_mfma_f32_16x16x32_bf16 v[114:117], v[162:165], v[178:181], v[114:117]
	v_mfma_f32_16x16x32_bf16 v[106:109], v[170:173], v[178:181], v[106:109]
	v_mfma_f32_16x16x32_bf16 v[98:101], v[162:165], v[186:189], v[98:101]
	v_mfma_f32_16x16x32_bf16 v[90:93], v[170:173], v[186:189], v[90:93]
	v_mfma_f32_16x16x32_bf16 v[82:85], v[162:165], v[194:197], v[82:85]
	v_mfma_f32_16x16x32_bf16 v[74:77], v[170:173], v[194:197], v[74:77]
	v_mfma_f32_16x16x32_bf16 v[70:73], v[162:165], v[202:205], v[70:73]
	v_mfma_f32_16x16x32_bf16 v[66:69], v[170:173], v[202:205], v[66:69]
	v_mfma_f32_16x16x32_bf16 v[114:117], v[166:169], v[182:185], v[114:117]
	v_mfma_f32_16x16x32_bf16 v[106:109], v[174:177], v[182:185], v[106:109]
	v_mfma_f32_16x16x32_bf16 v[98:101], v[166:169], v[190:193], v[98:101]
	v_mfma_f32_16x16x32_bf16 v[90:93], v[174:177], v[190:193], v[90:93]
	v_mfma_f32_16x16x32_bf16 v[82:85], v[166:169], v[198:201], v[82:85]
	v_mfma_f32_16x16x32_bf16 v[74:77], v[174:177], v[198:201], v[74:77]
	v_mfma_f32_16x16x32_bf16 v[70:73], v[166:169], v[206:209], v[70:73]
	v_mfma_f32_16x16x32_bf16 v[66:69], v[174:177], v[206:209], v[66:69]
	s_setprio 0
	s_barrier
; #define PG8_STAGE(bufoff, gbase, voff) do { _Pragma("unroll") for (int _i = 0; _i < 2; ++_i) \
;         __builtin_amdgcn_global_load_lds((const unsigned*)((const char*)(gbase) + (voff)[_i]), (PG8_LAS unsigned*)(lds + (bufoff) + ldsw + _i * 8192), 16, 0, 0); } while (0)
; #define PG8_LDA(dst, b, h) do { _Pragma("unroll") for (int m = 0; m < 4; ++m) _Pragma("unroll") for (int k = 0; k < 2; ++k) dst[m][k] = *(const PG8_LAS bf16x8*)(lds + PG8_SA(b, h) + aoff + m * 2048 + k * 1024); } while (0)
; #define PG8_MMA(ai, bj, At, Bt) do { __builtin_amdgcn_s_setprio(1); _Pragma("unroll") for (int m = 0; m < 4; ++m) _Pragma("unroll") for (int n = 0; n < 2; ++n) _Pragma("unroll") for (int k = 0; k < 2; ++k) \
;         acc[ai][bj][m][n] = __builtin_amdgcn_mfma_f32_16x16x32_bf16(Bt[n][k], At[m][k], acc[ai][bj][m][n], 0, 0, 0); __builtin_amdgcn_s_setprio(0); } while (0)
; #define PG8_WAIT_V(n) asm volatile("s_waitcnt vmcnt(" #n ")" ::: "memory")
; #define PG8_WAIT_L(n) asm volatile("s_waitcnt lgkmcnt(" #n ")" ::: "memory")
; #define PG8_BAR __builtin_amdgcn_s_barrier()
; #define PG8_SCHED __builtin_amdgcn_sched_barrier(0)
; template <class Epi, class Sched, bool ALIGN_EPI = false, bool SP2 = false>
; __device__ __forceinline__ void gemm_phase(PG8_LAS unsigned char* lds, const Gemm g, const Sched& S, const Epi& E, const int tid_in) {
;     ...
;         for (int t = 0; t < nt; t += 2) {
;             const bool last = (t == nt - 2);
;             const char* a1 = cA + (size_t)(t + 1) * kstep;
;             const char* a2 = last ? nA : cA + (size_t)(t + 2) * kstep; const char* b2 = last ? nB : cB + (size_t)(t + 2) * kstep;
;             const char* a3 = a2 + kstep; const char* b3 = b2 + kstep;
;             if (last && has_next) S.a_ready(nxt);
;     ...
;             PG8_WAIT_V(8); PG8_WAIT_L(0); PG8_BAR; PG8_MMA(0, 0, At, B0); PG8_MMA(0, 1, At, B1); PG8_BAR; PG8_SCHED;
;             PG8_LDA(At, 1, 1); PG8_STAGE(PG8_SB(1, 0), b3, voffB); PG8_STAGE(PG8_SB(1, 1), b3 + hstep, voffB); PG8_STAGE(PG8_SA(1, 0), a3, voffA);
;             PG8_WAIT_V(8); PG8_WAIT_L(0); PG8_BAR; PG8_MMA(1, 0, At, B0); PG8_MMA(1, 1, At, B1); PG8_BAR; PG8_SCHED;
	s_add_i32 s18, s70, s29
	s_mov_b32 m0, s18
	ds_read_b128 v[178:181], v145 offset:49152
	ds_read_b128 v[182:185], v145 offset:50176
	ds_read_b128 v[186:189], v145 offset:51200
	ds_read_b128 v[190:193], v145 offset:52224
	ds_read_b128 v[194:197], v145 offset:53248
	ds_read_b128 v[198:201], v145 offset:54272
	ds_read_b128 v[202:205], v145 offset:55296
	ds_read_b128 v[206:209], v145 offset:56320
	s_add_u32 s44, s22, 0x80
	s_addc_u32 s45, s23, 0
	global_load_lds_dwordx4 v0, s[44:45]
	s_add_i32 m0, s18, 0x2000
	s_add_u32 s18, s22, 0xb0080
	s_addc_u32 s19, s23, 0
	s_add_i32 s22, s71, s29
	global_load_lds_dwordx4 v134, s[44:45]
	s_mov_b32 m0, s22
	s_nop 0
	global_load_lds_dwordx4 v0, s[18:19]
	s_add_i32 m0, s22, 0x2000
	s_nop 0
	global_load_lds_dwordx4 v134, s[18:19]
	s_mov_b32 m0, s38
	s_nop 0
	s_add_u32 s44, s68, 0x80
	s_addc_u32 s45, s69, 0
	global_load_lds_dwordx4 v130, s[44:45]
	s_mov_b32 m0, s42
	s_nop 0
	global_load_lds_dwordx4 v132, s[44:45]
	s_waitcnt vmcnt(8)
	s_waitcnt lgkmcnt(0)
	s_barrier
	s_setprio 1
	s_waitcnt lgkmcnt(0)
	v_mfma_f32_16x16x32_bf16 v[62:65], v[146:149], v[178:181], v[62:65]
	v_mfma_f32_16x16x32_bf16 v[58:61], v[154:157], v[178:181], v[58:61]
	v_mfma_f32_16x16x32_bf16 v[54:57], v[146:149], v[186:189], v[54:57]
	v_mfma_f32_16x16x32_bf16 v[46:49], v[154:157], v[186:189], v[46:49]
	v_mfma_f32_16x16x32_bf16 v[38:41], v[146:149], v[194:197], v[38:41]
	v_mfma_f32_16x16x32_bf16 v[30:33], v[154:157], v[194:197], v[30:33]
	v_mfma_f32_16x16x32_bf16 v[22:25], v[146:149], v[202:205], v[22:25]
	v_mfma_f32_16x16x32_bf16 v[14:17], v[154:157], v[202:205], v[14:17]
	v_mfma_f32_16x16x32_bf16 v[62:65], v[150:153], v[182:185], v[62:65]
	v_mfma_f32_16x16x32_bf16 v[58:61], v[158:161], v[182:185], v[58:61]
	v_mfma_f32_16x16x32_bf16 v[54:57], v[150:153], v[190:193], v[54:57]
	v_mfma_f32_16x16x32_bf16 v[46:49], v[158:161], v[190:193], v[46:49]
	v_mfma_f32_16x16x32_bf16 v[38:41], v[150:153], v[198:201], v[38:41]
	v_mfma_f32_16x16x32_bf16 v[30:33], v[158:161], v[198:201], v[30:33]
	v_mfma_f32_16x16x32_bf16 v[22:25], v[150:153], v[206:209], v[22:25]
	v_mfma_f32_16x16x32_bf16 v[14:17], v[158:161], v[206:209], v[14:17]
	s_setprio 0
	s_setprio 1
	v_mfma_f32_16x16x32_bf16 v[50:53], v[162:165], v[178:181], v[50:53]
	v_mfma_f32_16x16x32_bf16 v[42:45], v[170:173], v[178:181], v[42:45]
	v_mfma_f32_16x16x32_bf16 v[34:37], v[162:165], v[186:189], v[34:37]
	v_mfma_f32_16x16x32_bf16 v[26:29], v[170:173], v[186:189], v[26:29]
	v_mfma_f32_16x16x32_bf16 v[18:21], v[162:165], v[194:197], v[18:21]
	v_mfma_f32_16x16x32_bf16 v[10:13], v[170:173], v[194:197], v[10:13]
	v_mfma_f32_16x16x32_bf16 v[6:9], v[162:165], v[202:205], v[6:9]
	v_mfma_f32_16x16x32_bf16 v[2:5], v[170:173], v[202:205], v[2:5]
	v_mfma_f32_16x16x32_bf16 v[50:53], v[166:169], v[182:185], v[50:53]
	v_mfma_f32_16x16x32_bf16 v[42:45], v[174:177], v[182:185], v[42:45]
	v_mfma_f32_16x16x32_bf16 v[34:37], v[166:169], v[190:193], v[34:37]
	v_mfma_f32_16x16x32_bf16 v[26:29], v[174:177], v[190:193], v[26:29]
	v_mfma_f32_16x16x32_bf16 v[18:21], v[166:169], v[198:201], v[18:21]
	v_mfma_f32_16x16x32_bf16 v[10:13], v[174:177], v[198:201], v[10:13]
	v_mfma_f32_16x16x32_bf16 v[6:9], v[166:169], v[206:209], v[6:9]
	v_mfma_f32_16x16x32_bf16 v[2:5], v[174:177], v[206:209], v[2:5]
	s_setprio 0
	s_add_i32 s64, s64, 2
	s_add_u32 s62, s62, 0x100
	s_addc_u32 s63, s63, 0
	s_mov_b64 s[18:19], s[20:21]
	s_cmp_gt_u32 s64, 41
	s_cbranch_scc1 .Lrotx_703
	s_add_u32 s20, s18, 0x100
	s_addc_u32 s21, s19, 0
	s_add_i32 s70, 0, 0x10000
	s_cmp_eq_u32 s64, 40
	s_cselect_b32 s69, s5, s21
	s_cselect_b32 s68, s4, s20
	v_add_u32_e32 v140, s70, v143
	s_cselect_b32 s23, s17, s63
	s_cselect_b32 s22, s16, s62
	s_add_i32 s71, 0, 0x14000
	s_barrier
	s_branch .Lrot_703
.Lrotx_703:
	s_barrier
	s_mov_b64 s[44:45], 0x80
	s_and_b64 vcc, exec, s[14:15]
	s_cbranch_vccz .LBB0_706
	s_barrier
